# phase-1 load segment reordered (B0 reads first via loop-invariant addr VGPR; SALU after reads/DMA), 2nd DMA of phase 1 moved to phase 2
# speedup vs baseline: 1.0098x; 1.0098x over previous
; #define PG8_STAGE(bufoff, gbase, voff) do { _Pragma("unroll") for (int _i = 0; _i < 2; ++_i) \
;         __builtin_amdgcn_global_load_lds((const unsigned*)((const char*)(gbase) + (voff)[_i]), (LAS unsigned*)(lds + (bufoff) + ldsw + _i * 8192), 16, 0, 0); } while (0)
; #define PG8_LDA(dst, b, h) do { _Pragma("unroll") for (int m = 0; m < 4; ++m) _Pragma("unroll") for (int k = 0; k < 2; ++k) dst[m][k] = *(const LAS bf16x8*)(lds + PG8_SA(b, h) + aoff + m * 2048 + k * 1024); } while (0)
; #define PG8_LDB(dst, b, h) do { _Pragma("unroll") for (int n = 0; n < 2; ++n) _Pragma("unroll") for (int k = 0; k < 2; ++k) dst[n][k] = *(const LAS bf16x8*)(lds + PG8_SB(b, h) + boff + n * 2048 + k * 1024); } while (0)
; #define PG8_MMA(ai, bj, At, Bt) do { __builtin_amdgcn_s_setprio(1); _Pragma("unroll") for (int m = 0; m < 4; ++m) _Pragma("unroll") for (int n = 0; n < 2; ++n) _Pragma("unroll") for (int k = 0; k < 2; ++k) \
;         acc[ai][bj][m][n] = __builtin_amdgcn_mfma_f32_16x16x32_bf16(Bt[n][k], At[m][k], acc[ai][bj][m][n], 0, 0, 0); __builtin_amdgcn_s_setprio(0); } while (0)
; #define PG8_WAIT_L(n) asm volatile("s_waitcnt lgkmcnt(" #n ")" ::: "memory")
; template <class Epi, class Sched>
; __device__ __forceinline__ void gemm_phase(LAS unsigned char* lds, const Gemm g, const Sched& S, const Epi& E, int tid) {
;     ...
;         const bool has_next = S.next(ui + 1, nxt);
;         const char* nA = has_next ? (const char*)g.A + (size_t)nxt.pm * tstep : cA; const char* nB = has_next ? (const char*)g.Bt + (size_t)nxt.pn * tstep : cB;
;         for (int t = 0; t < nt; t += 2) {
;             const bool last = (t == nt - 2);
;             const char* a1 = cA + (size_t)(t + 1) * kstep;
;             const char* a2 = last ? nA : cA + (size_t)(t + 2) * kstep; const char* b2 = last ? nB : cB + (size_t)(t + 2) * kstep;
;             const char* a3 = a2 + kstep; const char* b3 = b2 + kstep;
;             PG8_LDB(B0, 0, 0); PG8_SCHED; PG8_LDA(At, 0, 0); PG8_STAGE(PG8_SA(1, 1), a1 + hstep, voffA);
;             PG8_WAIT_L(8); PG8_BAR; PG8_WAIT_L(0); PG8_MMA(0, 0, At, B0); PG8_BAR; PG8_SCHED;
;             PG8_LDB(B1, 0, 1); PG8_STAGE(PG8_SB(0, 0), b2, voffB);
;             PG8_BAR; PG8_WAIT_L(0); PG8_MMA(0, 1, At, B1); PG8_BAR;
;             PG8_LDA(At, 0, 1); PG8_STAGE(PG8_SA(0, 0), a2, voffA);
;             PG8_BAR; PG8_WAIT_L(0); PG8_MMA(1, 0, At, B0); PG8_BAR; PG8_SCHED;
.LBB0_99:
	s_add_u32 vcc_lo, s44, 0x80
	s_addc_u32 vcc_hi, s45, 0
	s_add_u32 s96, s34, 0x100
	s_addc_u32 s65, s35, 0
	s_mov_b32 s34, 0
	v_add_u32_e32 v240, 0x10000, v141
	ds_read_b128 v[144:147], v240
	ds_read_b128 v[148:151], v240 offset:1024
	ds_read_b128 v[160:163], v240 offset:2048
	ds_read_b128 v[164:167], v240 offset:3072
	v_lshl_add_u64 v[152:153], vcc, 0, v[134:135]
	s_add_i32 m0, s88, 0xc000
	ds_read_b128 v[168:171], v143
	ds_read_b128 v[188:191], v143 offset:2048
	ds_read_b128 v[196:199], v143 offset:4096
	ds_read_b128 v[204:207], v143 offset:6144
	global_load_lds_dwordx4 v[152:153], off
	s_add_i32 s0, s34, 2
	s_add_u32 s1, vcc_lo, 0x80
	s_addc_u32 s35, vcc_hi, 0
	s_add_i32 s17, 0, 0x10000
	s_cmp_eq_u32 s95, s34
	s_cselect_b32 s34, s38, s1
	s_cselect_b32 s35, s39, s35
	s_cselect_b32 s45, s41, s65
	s_cselect_b32 s44, s40, s96
	s_waitcnt lgkmcnt(4)
	s_setprio 1
	s_barrier
	s_waitcnt lgkmcnt(0)
	v_mfma_f32_16x16x32_bf16 v[124:127], v[144:147], v[168:171], 0
	ds_read_b128 v[184:187], v143 offset:1024
	v_mfma_f32_16x16x32_bf16 v[120:123], v[160:163], v[168:171], 0
	ds_read_b128 v[192:195], v143 offset:3072
	v_mfma_f32_16x16x32_bf16 v[116:119], v[144:147], v[188:191], 0
	ds_read_b128 v[200:203], v143 offset:5120
	v_mfma_f32_16x16x32_bf16 v[112:115], v[160:163], v[188:191], 0
	ds_read_b128 v[208:211], v143 offset:7168
	v_mfma_f32_16x16x32_bf16 v[100:103], v[144:147], v[196:199], 0
	v_mfma_f32_16x16x32_bf16 v[96:99], v[160:163], v[196:199], 0
	v_mfma_f32_16x16x32_bf16 v[84:87], v[144:147], v[204:207], 0
	v_mfma_f32_16x16x32_bf16 v[80:83], v[160:163], v[204:207], 0
	s_waitcnt lgkmcnt(0)
	v_mfma_f32_16x16x32_bf16 v[124:127], v[148:151], v[184:187], v[124:127]
	v_mfma_f32_16x16x32_bf16 v[120:123], v[164:167], v[184:187], v[120:123]
	v_mfma_f32_16x16x32_bf16 v[116:119], v[148:151], v[192:195], v[116:119]
	v_mfma_f32_16x16x32_bf16 v[112:115], v[164:167], v[192:195], v[112:115]
	v_mfma_f32_16x16x32_bf16 v[100:103], v[148:151], v[200:203], v[100:103]
	v_mfma_f32_16x16x32_bf16 v[96:99], v[164:167], v[200:203], v[96:99]
	v_mfma_f32_16x16x32_bf16 v[84:87], v[148:151], v[208:211], v[84:87]
	v_mfma_f32_16x16x32_bf16 v[80:83], v[164:167], v[208:211], v[80:83]
	s_barrier
	s_setprio 0
	v_lshl_add_u64 v[238:239], vcc, 0, v[136:137]
	s_add_i32 m0, s88, 0xe000
	s_nop 0
	global_load_lds_dwordx4 v[238:239], off
	s_add_i32 s1, 0, 0x14000
	v_add_u32_e32 v152, s1, v141
	s_add_i32 s17, s17, s85
	ds_read_b128 v[212:215], v152
	ds_read_b128 v[216:219], v152 offset:1024
	ds_read_b128 v[220:223], v152 offset:2048
	ds_read_b128 v[224:227], v152 offset:3072
	v_lshl_add_u64 v[152:153], s[44:45], 0, v[154:155]
	s_mov_b32 m0, s17
	v_lshl_add_u64 v[228:229], s[44:45], 0, v[132:133]
	global_load_lds_dwordx4 v[152:153], off
	s_add_i32 m0, s17, 0x2000
	s_nop 0
	global_load_lds_dwordx4 v[228:229], off
	s_setprio 1
	s_barrier
	s_waitcnt lgkmcnt(0)
	v_mfma_f32_16x16x32_bf16 v[108:111], v[212:215], v[168:171], 0
	v_mfma_f32_16x16x32_bf16 v[104:107], v[220:223], v[168:171], 0
	v_mfma_f32_16x16x32_bf16 v[92:95], v[212:215], v[188:191], 0
	v_mfma_f32_16x16x32_bf16 v[88:91], v[220:223], v[188:191], 0
	v_mfma_f32_16x16x32_bf16 v[76:79], v[212:215], v[196:199], 0
	v_mfma_f32_16x16x32_bf16 v[72:75], v[220:223], v[196:199], 0
	s_mov_b32 m0, s88
	v_mfma_f32_16x16x32_bf16 v[68:71], v[212:215], v[204:207], 0
	v_lshl_add_u64 v[230:231], s[34:35], 0, v[128:129]
	v_mfma_f32_16x16x32_bf16 v[64:67], v[220:223], v[204:207], 0
	v_mfma_f32_16x16x32_bf16 v[108:111], v[216:219], v[184:187], v[108:111]
	v_mfma_f32_16x16x32_bf16 v[104:107], v[224:227], v[184:187], v[104:107]
	v_mfma_f32_16x16x32_bf16 v[92:95], v[216:219], v[192:195], v[92:95]
	v_mfma_f32_16x16x32_bf16 v[88:91], v[224:227], v[192:195], v[88:91]
	v_mfma_f32_16x16x32_bf16 v[76:79], v[216:219], v[200:203], v[76:79]
	v_mfma_f32_16x16x32_bf16 v[72:75], v[224:227], v[200:203], v[72:75]
	v_mfma_f32_16x16x32_bf16 v[68:71], v[216:219], v[208:211], v[68:71]
	v_mfma_f32_16x16x32_bf16 v[64:67], v[224:227], v[208:211], v[64:67]
	s_barrier
	s_setprio 0
	ds_read_b128 v[168:171], v143 offset:16384
	ds_read_b128 v[184:187], v143 offset:17408
	ds_read_b128 v[188:191], v143 offset:18432
	ds_read_b128 v[192:195], v143 offset:19456
	ds_read_b128 v[196:199], v143 offset:20480
	ds_read_b128 v[200:203], v143 offset:21504
	ds_read_b128 v[204:207], v143 offset:22528
	ds_read_b128 v[208:211], v143 offset:23552
	global_load_lds_dwordx4 v[230:231], off
	v_lshl_add_u64 v[232:233], s[34:35], 0, v[130:131]
	s_mov_b32 m0, s89
	s_nop 0
	global_load_lds_dwordx4 v[232:233], off
	s_setprio 1
	s_barrier
	s_waitcnt lgkmcnt(0)
	v_mfma_f32_16x16x32_bf16 v[60:63], v[144:147], v[168:171], 0
	v_mfma_f32_16x16x32_bf16 v[56:59], v[160:163], v[168:171], 0
	v_mfma_f32_16x16x32_bf16 v[52:55], v[144:147], v[188:191], 0
	v_mfma_f32_16x16x32_bf16 v[48:51], v[160:163], v[188:191], 0
	v_mfma_f32_16x16x32_bf16 v[36:39], v[144:147], v[196:199], 0
	v_mfma_f32_16x16x32_bf16 v[32:35], v[160:163], v[196:199], 0
	v_mfma_f32_16x16x32_bf16 v[20:23], v[144:147], v[204:207], 0
	v_mfma_f32_16x16x32_bf16 v[16:19], v[160:163], v[204:207], 0
	v_mfma_f32_16x16x32_bf16 v[60:63], v[148:151], v[184:187], v[60:63]
	v_mfma_f32_16x16x32_bf16 v[56:59], v[164:167], v[184:187], v[56:59]
	v_mfma_f32_16x16x32_bf16 v[52:55], v[148:151], v[192:195], v[52:55]
	v_mfma_f32_16x16x32_bf16 v[48:51], v[164:167], v[192:195], v[48:51]
	v_mfma_f32_16x16x32_bf16 v[36:39], v[148:151], v[200:203], v[36:39]
	v_mfma_f32_16x16x32_bf16 v[32:35], v[164:167], v[200:203], v[32:35]
	v_mfma_f32_16x16x32_bf16 v[20:23], v[148:151], v[208:211], v[20:23]
	v_mfma_f32_16x16x32_bf16 v[16:19], v[164:167], v[208:211], v[16:19]
	s_barrier
; #define PG8_STAGE(bufoff, gbase, voff) do { _Pragma("unroll") for (int _i = 0; _i < 2; ++_i) \
;         __builtin_amdgcn_global_load_lds((const unsigned*)((const char*)(gbase) + (voff)[_i]), (LAS unsigned*)(lds + (bufoff) + ldsw + _i * 8192), 16, 0, 0); } while (0)
; #define PG8_LDA(dst, b, h) do { _Pragma("unroll") for (int m = 0; m < 4; ++m) _Pragma("unroll") for (int k = 0; k < 2; ++k) dst[m][k] = *(const LAS bf16x8*)(lds + PG8_SA(b, h) + aoff + m * 2048 + k * 1024); } while (0)
; #define PG8_LDB(dst, b, h) do { _Pragma("unroll") for (int n = 0; n < 2; ++n) _Pragma("unroll") for (int k = 0; k < 2; ++k) dst[n][k] = *(const LAS bf16x8*)(lds + PG8_SB(b, h) + boff + n * 2048 + k * 1024); } while (0)
; #define PG8_MMA(ai, bj, At, Bt) do { __builtin_amdgcn_s_setprio(1); _Pragma("unroll") for (int m = 0; m < 4; ++m) _Pragma("unroll") for (int n = 0; n < 2; ++n) _Pragma("unroll") for (int k = 0; k < 2; ++k) \
;         acc[ai][bj][m][n] = __builtin_amdgcn_mfma_f32_16x16x32_bf16(Bt[n][k], At[m][k], acc[ai][bj][m][n], 0, 0, 0); __builtin_amdgcn_s_setprio(0); } while (0)
; #define PG8_WAIT_V(n) asm volatile("s_waitcnt vmcnt(" #n ")" ::: "memory")
; #define PG8_WAIT_L(n) asm volatile("s_waitcnt lgkmcnt(" #n ")" ::: "memory")
; #define PG8_BAR __builtin_amdgcn_s_barrier()
; #define PG8_SCHED __builtin_amdgcn_sched_barrier(0)
; template <class Epi, class Sched>
; __device__ __forceinline__ void gemm_phase(LAS unsigned char* lds, const Gemm g, const Sched& S, const Epi& E, int tid) {
;     ...
;             PG8_STAGE(PG8_SB(0, 1), b2 + hstep, voffB);
;             PG8_WAIT_V(6); PG8_BAR; PG8_MMA(1, 1, At, B1); PG8_BAR;
;             PG8_LDB(B0, 1, 0); PG8_SCHED; PG8_LDA(At, 1, 0); PG8_STAGE(PG8_SA(0, 1), a2 + hstep, voffA);
;             PG8_WAIT_L(8); PG8_BAR; PG8_WAIT_L(0); PG8_MMA(0, 0, At, B0); PG8_BAR; PG8_SCHED;
;             PG8_LDB(B1, 1, 1); PG8_STAGE(PG8_SB(1, 0), b3, voffB);
;             PG8_BAR; PG8_WAIT_L(0); PG8_MMA(0, 1, At, B1); PG8_BAR;
;             PG8_LDA(At, 1, 1); PG8_STAGE(PG8_SA(1, 0), a3, voffA);
	s_setprio 0
	s_add_u32 s44, s44, s6
	s_addc_u32 s45, s45, 0
	s_add_i32 s1, s1, s85
	v_lshl_add_u64 v[234:235], s[44:45], 0, v[154:155]
	s_mov_b32 m0, s1
	v_lshl_add_u64 v[236:237], s[44:45], 0, v[132:133]
	global_load_lds_dwordx4 v[234:235], off
	s_add_i32 m0, s1, 0x2000
	s_nop 0
	global_load_lds_dwordx4 v[236:237], off
	s_waitcnt vmcnt(24)
	s_setprio 1
	s_barrier
	v_mfma_f32_16x16x32_bf16 v[44:47], v[212:215], v[168:171], 0
	v_mfma_f32_16x16x32_bf16 v[40:43], v[220:223], v[168:171], 0
	v_mfma_f32_16x16x32_bf16 v[28:31], v[212:215], v[188:191], 0
	v_mfma_f32_16x16x32_bf16 v[24:27], v[220:223], v[188:191], 0
	v_mfma_f32_16x16x32_bf16 v[12:15], v[212:215], v[196:199], 0
	v_mfma_f32_16x16x32_bf16 v[8:11], v[220:223], v[196:199], 0
	s_add_i32 s1, 0, 0x18000
	v_mfma_f32_16x16x32_bf16 v[4:7], v[212:215], v[204:207], 0
	v_add_u32_e32 v164, s1, v141
	v_mfma_f32_16x16x32_bf16 v[0:3], v[220:223], v[204:207], 0
	v_mfma_f32_16x16x32_bf16 v[44:47], v[216:219], v[184:187], v[44:47]
	v_mfma_f32_16x16x32_bf16 v[40:43], v[224:227], v[184:187], v[40:43]
	v_mfma_f32_16x16x32_bf16 v[28:31], v[216:219], v[192:195], v[28:31]
	v_mfma_f32_16x16x32_bf16 v[24:27], v[224:227], v[192:195], v[24:27]
	v_mfma_f32_16x16x32_bf16 v[12:15], v[216:219], v[200:203], v[12:15]
	v_mfma_f32_16x16x32_bf16 v[8:11], v[224:227], v[200:203], v[8:11]
	v_mfma_f32_16x16x32_bf16 v[4:7], v[216:219], v[208:211], v[4:7]
	v_mfma_f32_16x16x32_bf16 v[0:3], v[224:227], v[208:211], v[0:3]
	s_barrier
	s_setprio 0
	ds_read_b128 v[144:147], v164
	ds_read_b128 v[148:151], v164 offset:1024
	ds_read_b128 v[160:163], v164 offset:2048
	ds_read_b128 v[164:167], v164 offset:3072
	s_add_u32 s34, s34, s6
	s_addc_u32 s35, s35, 0
	s_mov_b32 m0, s90
	v_lshl_add_u64 v[212:213], s[34:35], 0, v[128:129]
	ds_read_b128 v[168:171], v143 offset:32768
	ds_read_b128 v[188:191], v143 offset:34816
	ds_read_b128 v[196:199], v143 offset:36864
	ds_read_b128 v[204:207], v143 offset:38912
	global_load_lds_dwordx4 v[212:213], off
	s_waitcnt lgkmcnt(4)
	s_setprio 1
	s_barrier
	s_waitcnt lgkmcnt(0)
	v_mfma_f32_16x16x32_bf16 v[124:127], v[144:147], v[168:171], v[124:127]
	ds_read_b128 v[184:187], v143 offset:33792
	v_mfma_f32_16x16x32_bf16 v[120:123], v[160:163], v[168:171], v[120:123]
	ds_read_b128 v[192:195], v143 offset:35840
	v_mfma_f32_16x16x32_bf16 v[116:119], v[144:147], v[188:191], v[116:119]
	ds_read_b128 v[200:203], v143 offset:37888
	v_mfma_f32_16x16x32_bf16 v[112:115], v[160:163], v[188:191], v[112:115]
	ds_read_b128 v[208:211], v143 offset:39936
	v_mfma_f32_16x16x32_bf16 v[100:103], v[144:147], v[196:199], v[100:103]
	v_mfma_f32_16x16x32_bf16 v[96:99], v[160:163], v[196:199], v[96:99]
	v_mfma_f32_16x16x32_bf16 v[84:87], v[144:147], v[204:207], v[84:87]
	v_mfma_f32_16x16x32_bf16 v[80:83], v[160:163], v[204:207], v[80:83]
	s_waitcnt lgkmcnt(0)
	v_mfma_f32_16x16x32_bf16 v[124:127], v[148:151], v[184:187], v[124:127]
	v_mfma_f32_16x16x32_bf16 v[120:123], v[164:167], v[184:187], v[120:123]
	v_mfma_f32_16x16x32_bf16 v[116:119], v[148:151], v[192:195], v[116:119]
	v_mfma_f32_16x16x32_bf16 v[112:115], v[164:167], v[192:195], v[112:115]
	v_mfma_f32_16x16x32_bf16 v[100:103], v[148:151], v[200:203], v[100:103]
	v_mfma_f32_16x16x32_bf16 v[96:99], v[164:167], v[200:203], v[96:99]
	v_mfma_f32_16x16x32_bf16 v[84:87], v[148:151], v[208:211], v[84:87]
	v_mfma_f32_16x16x32_bf16 v[80:83], v[164:167], v[208:211], v[80:83]
	s_barrier
	s_setprio 0
	v_lshl_add_u64 v[238:239], s[34:35], 0, v[130:131]
	s_mov_b32 m0, s91
	s_nop 0
	global_load_lds_dwordx4 v[238:239], off
	s_add_i32 s17, 0, 0x1c000
	s_add_i32 s1, s1, s85
	v_add_u32_e32 v183, s17, v141
	v_lshl_add_u64 v[152:153], v[152:153], 0, s[8:9]
	s_mov_b32 m0, s1
	ds_read_b128 v[212:215], v183
	ds_read_b128 v[216:219], v183 offset:1024
	ds_read_b128 v[220:223], v183 offset:2048
	ds_read_b128 v[224:227], v183 offset:3072
	global_load_lds_dwordx4 v[152:153], off
	v_lshl_add_u64 v[152:153], v[228:229], 0, s[8:9]
	s_add_i32 m0, s1, 0x2000
	s_nop 0
	global_load_lds_dwordx4 v[152:153], off
	s_waitcnt vmcnt(10)
	s_setprio 1
	s_barrier
	s_waitcnt lgkmcnt(0)
	v_mfma_f32_16x16x32_bf16 v[108:111], v[212:215], v[168:171], v[108:111]
	v_mfma_f32_16x16x32_bf16 v[104:107], v[220:223], v[168:171], v[104:107]
	v_mfma_f32_16x16x32_bf16 v[92:95], v[212:215], v[188:191], v[92:95]
	v_mfma_f32_16x16x32_bf16 v[88:91], v[220:223], v[188:191], v[88:91]
	v_mfma_f32_16x16x32_bf16 v[76:79], v[212:215], v[196:199], v[76:79]
	v_mfma_f32_16x16x32_bf16 v[72:75], v[220:223], v[196:199], v[72:75]
	s_mov_b32 m0, s92
	v_mfma_f32_16x16x32_bf16 v[68:71], v[212:215], v[204:207], v[68:71]
	v_lshl_add_u64 v[152:153], v[230:231], 0, s[8:9]
	v_mfma_f32_16x16x32_bf16 v[64:67], v[220:223], v[204:207], v[64:67]
	v_mfma_f32_16x16x32_bf16 v[108:111], v[216:219], v[184:187], v[108:111]
	v_mfma_f32_16x16x32_bf16 v[104:107], v[224:227], v[184:187], v[104:107]
	v_mfma_f32_16x16x32_bf16 v[92:95], v[216:219], v[192:195], v[92:95]
	v_mfma_f32_16x16x32_bf16 v[88:91], v[224:227], v[192:195], v[88:91]
	v_mfma_f32_16x16x32_bf16 v[76:79], v[216:219], v[200:203], v[76:79]
	v_mfma_f32_16x16x32_bf16 v[72:75], v[224:227], v[200:203], v[72:75]
	v_mfma_f32_16x16x32_bf16 v[68:71], v[216:219], v[208:211], v[68:71]
	v_mfma_f32_16x16x32_bf16 v[64:67], v[224:227], v[208:211], v[64:67]
	s_barrier
	s_setprio 0
	ds_read_b128 v[168:171], v143 offset:49152
	ds_read_b128 v[184:187], v143 offset:50176
	ds_read_b128 v[188:191], v143 offset:51200
	ds_read_b128 v[192:195], v143 offset:52224
	ds_read_b128 v[196:199], v143 offset:53248
	ds_read_b128 v[200:203], v143 offset:54272
	ds_read_b128 v[204:207], v143 offset:55296
	ds_read_b128 v[208:211], v143 offset:56320
	global_load_lds_dwordx4 v[152:153], off
	v_lshl_add_u64 v[152:153], v[232:233], 0, s[8:9]
	s_mov_b32 m0, s93
	s_nop 0
	global_load_lds_dwordx4 v[152:153], off
	s_setprio 1
	s_barrier
; #define PG8_STAGE(bufoff, gbase, voff) do { _Pragma("unroll") for (int _i = 0; _i < 2; ++_i) \
;         __builtin_amdgcn_global_load_lds((const unsigned*)((const char*)(gbase) + (voff)[_i]), (LAS unsigned*)(lds + (bufoff) + ldsw + _i * 8192), 16, 0, 0); } while (0)
; #define PG8_LDA(dst, b, h) do { _Pragma("unroll") for (int m = 0; m < 4; ++m) _Pragma("unroll") for (int k = 0; k < 2; ++k) dst[m][k] = *(const LAS bf16x8*)(lds + PG8_SA(b, h) + aoff + m * 2048 + k * 1024); } while (0)
; #define PG8_LDB(dst, b, h) do { _Pragma("unroll") for (int n = 0; n < 2; ++n) _Pragma("unroll") for (int k = 0; k < 2; ++k) dst[n][k] = *(const LAS bf16x8*)(lds + PG8_SB(b, h) + boff + n * 2048 + k * 1024); } while (0)
; #define PG8_MMA(ai, bj, At, Bt) do { __builtin_amdgcn_s_setprio(1); _Pragma("unroll") for (int m = 0; m < 4; ++m) _Pragma("unroll") for (int n = 0; n < 2; ++n) _Pragma("unroll") for (int k = 0; k < 2; ++k) \
;         acc[ai][bj][m][n] = __builtin_amdgcn_mfma_f32_16x16x32_bf16(Bt[n][k], At[m][k], acc[ai][bj][m][n], 0, 0, 0); __builtin_amdgcn_s_setprio(0); } while (0)
; #define PG8_WAIT_V(n) asm volatile("s_waitcnt vmcnt(" #n ")" ::: "memory")
; #define PG8_WAIT_L(n) asm volatile("s_waitcnt lgkmcnt(" #n ")" ::: "memory")
; #define PG8_BAR __builtin_amdgcn_s_barrier()
; #define PG8_SCHED __builtin_amdgcn_sched_barrier(0)
; template <class Epi, class Sched>
; __device__ __forceinline__ void gemm_phase(LAS unsigned char* lds, const Gemm g, const Sched& S, const Epi& E, int tid) {
;     ...
;         for (int t = 0; t < nt; t += 2) {
;             const bool last = (t == nt - 2);
;             const char* a1 = cA + (size_t)(t + 1) * kstep;
;             const char* a2 = last ? nA : cA + (size_t)(t + 2) * kstep; const char* b2 = last ? nB : cB + (size_t)(t + 2) * kstep;
;             const char* a3 = a2 + kstep; const char* b3 = b2 + kstep;
;             PG8_LDB(B0, 0, 0); PG8_SCHED; PG8_LDA(At, 0, 0); PG8_STAGE(PG8_SA(1, 1), a1 + hstep, voffA);
;             PG8_WAIT_L(8); PG8_BAR; PG8_WAIT_L(0); PG8_MMA(0, 0, At, B0); PG8_BAR; PG8_SCHED;
;             PG8_LDB(B1, 0, 1); PG8_STAGE(PG8_SB(0, 0), b2, voffB);
;     ...
;             PG8_BAR; PG8_WAIT_L(0); PG8_MMA(1, 0, At, B0); PG8_BAR; PG8_SCHED;
;             PG8_STAGE(PG8_SB(1, 1), b3 + hstep, voffB);
;             PG8_WAIT_V(6); PG8_BAR; PG8_MMA(1, 1, At, B1); PG8_BAR;
	s_waitcnt lgkmcnt(0)
	v_mfma_f32_16x16x32_bf16 v[60:63], v[144:147], v[168:171], v[60:63]
	v_mfma_f32_16x16x32_bf16 v[56:59], v[160:163], v[168:171], v[56:59]
	v_mfma_f32_16x16x32_bf16 v[52:55], v[144:147], v[188:191], v[52:55]
	v_mfma_f32_16x16x32_bf16 v[48:51], v[160:163], v[188:191], v[48:51]
	v_mfma_f32_16x16x32_bf16 v[36:39], v[144:147], v[196:199], v[36:39]
	v_mfma_f32_16x16x32_bf16 v[32:35], v[160:163], v[196:199], v[32:35]
	v_mfma_f32_16x16x32_bf16 v[20:23], v[144:147], v[204:207], v[20:23]
	v_mfma_f32_16x16x32_bf16 v[16:19], v[160:163], v[204:207], v[16:19]
	v_mfma_f32_16x16x32_bf16 v[60:63], v[148:151], v[184:187], v[60:63]
	v_mfma_f32_16x16x32_bf16 v[56:59], v[164:167], v[184:187], v[56:59]
	v_mfma_f32_16x16x32_bf16 v[52:55], v[148:151], v[192:195], v[52:55]
	v_mfma_f32_16x16x32_bf16 v[48:51], v[164:167], v[192:195], v[48:51]
	v_mfma_f32_16x16x32_bf16 v[36:39], v[148:151], v[200:203], v[36:39]
	v_mfma_f32_16x16x32_bf16 v[32:35], v[164:167], v[200:203], v[32:35]
	v_mfma_f32_16x16x32_bf16 v[20:23], v[148:151], v[208:211], v[20:23]
	v_mfma_f32_16x16x32_bf16 v[16:19], v[164:167], v[208:211], v[16:19]
	s_barrier
	s_setprio 0
	s_add_i32 s1, s17, s85
	v_lshl_add_u64 v[144:145], v[234:235], 0, s[8:9]
	s_mov_b32 m0, s1
	s_nop 0
	global_load_lds_dwordx4 v[144:145], off
	v_lshl_add_u64 v[144:145], v[236:237], 0, s[8:9]
	s_add_i32 m0, s1, 0x2000
	s_nop 0
	global_load_lds_dwordx4 v[144:145], off
	s_waitcnt vmcnt(6)
	s_setprio 1
	s_barrier
	v_mfma_f32_16x16x32_bf16 v[44:47], v[212:215], v[168:171], v[44:47]
	v_mfma_f32_16x16x32_bf16 v[40:43], v[220:223], v[168:171], v[40:43]
	v_mfma_f32_16x16x32_bf16 v[28:31], v[212:215], v[188:191], v[28:31]
	v_mfma_f32_16x16x32_bf16 v[24:27], v[220:223], v[188:191], v[24:27]
	v_mfma_f32_16x16x32_bf16 v[12:15], v[212:215], v[196:199], v[12:15]
	v_mfma_f32_16x16x32_bf16 v[8:11], v[220:223], v[196:199], v[8:11]
	s_add_u32 vcc_lo, vcc_lo, 0x100
	v_mfma_f32_16x16x32_bf16 v[4:7], v[212:215], v[204:207], v[4:7]
	s_addc_u32 vcc_hi, vcc_hi, 0
	v_mfma_f32_16x16x32_bf16 v[0:3], v[220:223], v[204:207], v[0:3]
	s_add_u32 s96, s96, 0x100
	v_mfma_f32_16x16x32_bf16 v[44:47], v[216:219], v[184:187], v[44:47]
	s_addc_u32 s65, s65, 0
	v_mfma_f32_16x16x32_bf16 v[40:43], v[224:227], v[184:187], v[40:43]
	s_cmp_ge_u32 s0, s94
	v_mfma_f32_16x16x32_bf16 v[28:31], v[216:219], v[192:195], v[28:31]
	s_mov_b32 s34, s0
	v_mfma_f32_16x16x32_bf16 v[24:27], v[224:227], v[192:195], v[24:27]
	v_mfma_f32_16x16x32_bf16 v[12:15], v[216:219], v[200:203], v[12:15]
	v_mfma_f32_16x16x32_bf16 v[8:11], v[224:227], v[200:203], v[8:11]
	v_mfma_f32_16x16x32_bf16 v[4:7], v[216:219], v[208:211], v[4:7]
	v_mfma_f32_16x16x32_bf16 v[0:3], v[224:227], v[208:211], v[0:3]
	s_barrier
	s_setprio 0
	s_cbranch_scc1 .Lpeel_exit_plain
.LBB0_100:
	ds_read_b128 v[144:147], v240
	ds_read_b128 v[148:151], v240 offset:1024
	ds_read_b128 v[160:163], v240 offset:2048
	ds_read_b128 v[164:167], v240 offset:3072
	v_lshl_add_u64 v[152:153], vcc, 0, v[134:135]
	s_add_i32 m0, s88, 0xc000
	ds_read_b128 v[168:171], v143
	ds_read_b128 v[188:191], v143 offset:2048
	ds_read_b128 v[196:199], v143 offset:4096
	ds_read_b128 v[204:207], v143 offset:6144
	global_load_lds_dwordx4 v[152:153], off
	s_add_i32 s0, s34, 2
	s_add_u32 s1, vcc_lo, 0x80
	s_addc_u32 s35, vcc_hi, 0
	s_add_i32 s17, 0, 0x10000
	s_cmp_eq_u32 s95, s34
	s_cselect_b32 s34, s38, s1
	s_cselect_b32 s35, s39, s35
	s_cselect_b32 s45, s41, s65
	s_cselect_b32 s44, s40, s96
	s_waitcnt lgkmcnt(4)
	s_setprio 1
	s_barrier
	s_waitcnt lgkmcnt(0)
	v_mfma_f32_16x16x32_bf16 v[124:127], v[144:147], v[168:171], v[124:127]
	ds_read_b128 v[184:187], v143 offset:1024
	v_mfma_f32_16x16x32_bf16 v[120:123], v[160:163], v[168:171], v[120:123]
	ds_read_b128 v[192:195], v143 offset:3072
	v_mfma_f32_16x16x32_bf16 v[116:119], v[144:147], v[188:191], v[116:119]
	ds_read_b128 v[200:203], v143 offset:5120
	v_mfma_f32_16x16x32_bf16 v[112:115], v[160:163], v[188:191], v[112:115]
	ds_read_b128 v[208:211], v143 offset:7168
	v_mfma_f32_16x16x32_bf16 v[100:103], v[144:147], v[196:199], v[100:103]
	v_mfma_f32_16x16x32_bf16 v[96:99], v[160:163], v[196:199], v[96:99]
	v_mfma_f32_16x16x32_bf16 v[84:87], v[144:147], v[204:207], v[84:87]
	v_mfma_f32_16x16x32_bf16 v[80:83], v[160:163], v[204:207], v[80:83]
	s_waitcnt lgkmcnt(0)
	v_mfma_f32_16x16x32_bf16 v[124:127], v[148:151], v[184:187], v[124:127]
	v_mfma_f32_16x16x32_bf16 v[120:123], v[164:167], v[184:187], v[120:123]
	v_mfma_f32_16x16x32_bf16 v[116:119], v[148:151], v[192:195], v[116:119]
	v_mfma_f32_16x16x32_bf16 v[112:115], v[164:167], v[192:195], v[112:115]
	v_mfma_f32_16x16x32_bf16 v[100:103], v[148:151], v[200:203], v[100:103]
	v_mfma_f32_16x16x32_bf16 v[96:99], v[164:167], v[200:203], v[96:99]
	v_mfma_f32_16x16x32_bf16 v[84:87], v[148:151], v[208:211], v[84:87]
	v_mfma_f32_16x16x32_bf16 v[80:83], v[164:167], v[208:211], v[80:83]
	s_barrier
	s_setprio 0
	v_lshl_add_u64 v[238:239], vcc, 0, v[136:137]
	s_add_i32 m0, s88, 0xe000
	s_nop 0
	global_load_lds_dwordx4 v[238:239], off
	s_add_i32 s1, 0, 0x14000
	v_add_u32_e32 v152, s1, v141
	s_add_i32 s17, s17, s85
	ds_read_b128 v[212:215], v152
	ds_read_b128 v[216:219], v152 offset:1024
	ds_read_b128 v[220:223], v152 offset:2048
	ds_read_b128 v[224:227], v152 offset:3072
	v_lshl_add_u64 v[152:153], s[44:45], 0, v[154:155]
	s_mov_b32 m0, s17
	v_lshl_add_u64 v[228:229], s[44:45], 0, v[132:133]
	global_load_lds_dwordx4 v[152:153], off
	s_add_i32 m0, s17, 0x2000
	s_nop 0
	global_load_lds_dwordx4 v[228:229], off
	s_setprio 1
	s_barrier
; #define PG8_STAGE(bufoff, gbase, voff) do { _Pragma("unroll") for (int _i = 0; _i < 2; ++_i) \
;         __builtin_amdgcn_global_load_lds((const unsigned*)((const char*)(gbase) + (voff)[_i]), (LAS unsigned*)(lds + (bufoff) + ldsw + _i * 8192), 16, 0, 0); } while (0)
; #define PG8_LDA(dst, b, h) do { _Pragma("unroll") for (int m = 0; m < 4; ++m) _Pragma("unroll") for (int k = 0; k < 2; ++k) dst[m][k] = *(const LAS bf16x8*)(lds + PG8_SA(b, h) + aoff + m * 2048 + k * 1024); } while (0)
; #define PG8_LDB(dst, b, h) do { _Pragma("unroll") for (int n = 0; n < 2; ++n) _Pragma("unroll") for (int k = 0; k < 2; ++k) dst[n][k] = *(const LAS bf16x8*)(lds + PG8_SB(b, h) + boff + n * 2048 + k * 1024); } while (0)
; #define PG8_MMA(ai, bj, At, Bt) do { __builtin_amdgcn_s_setprio(1); _Pragma("unroll") for (int m = 0; m < 4; ++m) _Pragma("unroll") for (int n = 0; n < 2; ++n) _Pragma("unroll") for (int k = 0; k < 2; ++k) \
;         acc[ai][bj][m][n] = __builtin_amdgcn_mfma_f32_16x16x32_bf16(Bt[n][k], At[m][k], acc[ai][bj][m][n], 0, 0, 0); __builtin_amdgcn_s_setprio(0); } while (0)
; #define PG8_WAIT_V(n) asm volatile("s_waitcnt vmcnt(" #n ")" ::: "memory")
; #define PG8_WAIT_L(n) asm volatile("s_waitcnt lgkmcnt(" #n ")" ::: "memory")
; #define PG8_BAR __builtin_amdgcn_s_barrier()
; #define PG8_SCHED __builtin_amdgcn_sched_barrier(0)
; template <class Epi, class Sched>
; __device__ __forceinline__ void gemm_phase(LAS unsigned char* lds, const Gemm g, const Sched& S, const Epi& E, int tid) {
;     ...
;             PG8_BAR; PG8_WAIT_L(0); PG8_MMA(0, 1, At, B1); PG8_BAR;
;             PG8_LDA(At, 0, 1); PG8_STAGE(PG8_SA(0, 0), a2, voffA);
;             PG8_BAR; PG8_WAIT_L(0); PG8_MMA(1, 0, At, B0); PG8_BAR; PG8_SCHED;
;             PG8_STAGE(PG8_SB(0, 1), b2 + hstep, voffB);
;             PG8_WAIT_V(6); PG8_BAR; PG8_MMA(1, 1, At, B1); PG8_BAR;
;             PG8_LDB(B0, 1, 0); PG8_SCHED; PG8_LDA(At, 1, 0); PG8_STAGE(PG8_SA(0, 1), a2 + hstep, voffA);
	s_waitcnt lgkmcnt(0)
	v_mfma_f32_16x16x32_bf16 v[108:111], v[212:215], v[168:171], v[108:111]
	v_mfma_f32_16x16x32_bf16 v[104:107], v[220:223], v[168:171], v[104:107]
	v_mfma_f32_16x16x32_bf16 v[92:95], v[212:215], v[188:191], v[92:95]
	v_mfma_f32_16x16x32_bf16 v[88:91], v[220:223], v[188:191], v[88:91]
	v_mfma_f32_16x16x32_bf16 v[76:79], v[212:215], v[196:199], v[76:79]
	v_mfma_f32_16x16x32_bf16 v[72:75], v[220:223], v[196:199], v[72:75]
	s_mov_b32 m0, s88
	v_mfma_f32_16x16x32_bf16 v[68:71], v[212:215], v[204:207], v[68:71]
	v_lshl_add_u64 v[230:231], s[34:35], 0, v[128:129]
	v_mfma_f32_16x16x32_bf16 v[64:67], v[220:223], v[204:207], v[64:67]
	v_mfma_f32_16x16x32_bf16 v[108:111], v[216:219], v[184:187], v[108:111]
	v_mfma_f32_16x16x32_bf16 v[104:107], v[224:227], v[184:187], v[104:107]
	v_mfma_f32_16x16x32_bf16 v[92:95], v[216:219], v[192:195], v[92:95]
	v_mfma_f32_16x16x32_bf16 v[88:91], v[224:227], v[192:195], v[88:91]
	v_mfma_f32_16x16x32_bf16 v[76:79], v[216:219], v[200:203], v[76:79]
	v_mfma_f32_16x16x32_bf16 v[72:75], v[224:227], v[200:203], v[72:75]
	v_mfma_f32_16x16x32_bf16 v[68:71], v[216:219], v[208:211], v[68:71]
	v_mfma_f32_16x16x32_bf16 v[64:67], v[224:227], v[208:211], v[64:67]
	s_barrier
	s_setprio 0
	ds_read_b128 v[168:171], v143 offset:16384
	ds_read_b128 v[184:187], v143 offset:17408
	ds_read_b128 v[188:191], v143 offset:18432
	ds_read_b128 v[192:195], v143 offset:19456
	ds_read_b128 v[196:199], v143 offset:20480
	ds_read_b128 v[200:203], v143 offset:21504
	ds_read_b128 v[204:207], v143 offset:22528
	ds_read_b128 v[208:211], v143 offset:23552
	global_load_lds_dwordx4 v[230:231], off
	v_lshl_add_u64 v[232:233], s[34:35], 0, v[130:131]
	s_mov_b32 m0, s89
	s_nop 0
	global_load_lds_dwordx4 v[232:233], off
	s_setprio 1
	s_barrier
	s_waitcnt lgkmcnt(0)
	v_mfma_f32_16x16x32_bf16 v[60:63], v[144:147], v[168:171], v[60:63]
	v_mfma_f32_16x16x32_bf16 v[56:59], v[160:163], v[168:171], v[56:59]
	v_mfma_f32_16x16x32_bf16 v[52:55], v[144:147], v[188:191], v[52:55]
	v_mfma_f32_16x16x32_bf16 v[48:51], v[160:163], v[188:191], v[48:51]
	v_mfma_f32_16x16x32_bf16 v[36:39], v[144:147], v[196:199], v[36:39]
	v_mfma_f32_16x16x32_bf16 v[32:35], v[160:163], v[196:199], v[32:35]
	v_mfma_f32_16x16x32_bf16 v[20:23], v[144:147], v[204:207], v[20:23]
	v_mfma_f32_16x16x32_bf16 v[16:19], v[160:163], v[204:207], v[16:19]
	v_mfma_f32_16x16x32_bf16 v[60:63], v[148:151], v[184:187], v[60:63]
	v_mfma_f32_16x16x32_bf16 v[56:59], v[164:167], v[184:187], v[56:59]
	v_mfma_f32_16x16x32_bf16 v[52:55], v[148:151], v[192:195], v[52:55]
	v_mfma_f32_16x16x32_bf16 v[48:51], v[164:167], v[192:195], v[48:51]
	v_mfma_f32_16x16x32_bf16 v[36:39], v[148:151], v[200:203], v[36:39]
	v_mfma_f32_16x16x32_bf16 v[32:35], v[164:167], v[200:203], v[32:35]
	v_mfma_f32_16x16x32_bf16 v[20:23], v[148:151], v[208:211], v[20:23]
	v_mfma_f32_16x16x32_bf16 v[16:19], v[164:167], v[208:211], v[16:19]
	s_barrier
	s_setprio 0
	s_add_u32 s44, s44, s6
	s_addc_u32 s45, s45, 0
	s_add_i32 s1, s1, s85
	v_lshl_add_u64 v[234:235], s[44:45], 0, v[154:155]
	s_mov_b32 m0, s1
	v_lshl_add_u64 v[236:237], s[44:45], 0, v[132:133]
	global_load_lds_dwordx4 v[234:235], off
	s_add_i32 m0, s1, 0x2000
	s_nop 0
	global_load_lds_dwordx4 v[236:237], off
	s_waitcnt vmcnt(6)
	s_setprio 1
	s_barrier
	v_mfma_f32_16x16x32_bf16 v[44:47], v[212:215], v[168:171], v[44:47]
	v_mfma_f32_16x16x32_bf16 v[40:43], v[220:223], v[168:171], v[40:43]
	v_mfma_f32_16x16x32_bf16 v[28:31], v[212:215], v[188:191], v[28:31]
	v_mfma_f32_16x16x32_bf16 v[24:27], v[220:223], v[188:191], v[24:27]
	v_mfma_f32_16x16x32_bf16 v[12:15], v[212:215], v[196:199], v[12:15]
	v_mfma_f32_16x16x32_bf16 v[8:11], v[220:223], v[196:199], v[8:11]
	s_add_i32 s1, 0, 0x18000
	v_mfma_f32_16x16x32_bf16 v[4:7], v[212:215], v[204:207], v[4:7]
	v_add_u32_e32 v164, s1, v141
	v_mfma_f32_16x16x32_bf16 v[0:3], v[220:223], v[204:207], v[0:3]
	v_mfma_f32_16x16x32_bf16 v[44:47], v[216:219], v[184:187], v[44:47]
	v_mfma_f32_16x16x32_bf16 v[40:43], v[224:227], v[184:187], v[40:43]
	v_mfma_f32_16x16x32_bf16 v[28:31], v[216:219], v[192:195], v[28:31]
	v_mfma_f32_16x16x32_bf16 v[24:27], v[224:227], v[192:195], v[24:27]
	v_mfma_f32_16x16x32_bf16 v[12:15], v[216:219], v[200:203], v[12:15]
	v_mfma_f32_16x16x32_bf16 v[8:11], v[224:227], v[200:203], v[8:11]
	v_mfma_f32_16x16x32_bf16 v[4:7], v[216:219], v[208:211], v[4:7]
	v_mfma_f32_16x16x32_bf16 v[0:3], v[224:227], v[208:211], v[0:3]
	s_barrier
	s_setprio 0
	ds_read_b128 v[144:147], v164
	ds_read_b128 v[148:151], v164 offset:1024
	ds_read_b128 v[160:163], v164 offset:2048
	ds_read_b128 v[164:167], v164 offset:3072
	s_add_u32 s34, s34, s6
	s_addc_u32 s35, s35, 0
	s_mov_b32 m0, s90
	v_lshl_add_u64 v[212:213], s[34:35], 0, v[128:129]
	ds_read_b128 v[168:171], v143 offset:32768
	ds_read_b128 v[188:191], v143 offset:34816
	ds_read_b128 v[196:199], v143 offset:36864
	ds_read_b128 v[204:207], v143 offset:38912
	global_load_lds_dwordx4 v[212:213], off
	s_waitcnt lgkmcnt(4)
	s_setprio 1
	s_barrier
; #define PG8_STAGE(bufoff, gbase, voff) do { _Pragma("unroll") for (int _i = 0; _i < 2; ++_i) \
;         __builtin_amdgcn_global_load_lds((const unsigned*)((const char*)(gbase) + (voff)[_i]), (LAS unsigned*)(lds + (bufoff) + ldsw + _i * 8192), 16, 0, 0); } while (0)
; #define PG8_LDA(dst, b, h) do { _Pragma("unroll") for (int m = 0; m < 4; ++m) _Pragma("unroll") for (int k = 0; k < 2; ++k) dst[m][k] = *(const LAS bf16x8*)(lds + PG8_SA(b, h) + aoff + m * 2048 + k * 1024); } while (0)
; #define PG8_LDB(dst, b, h) do { _Pragma("unroll") for (int n = 0; n < 2; ++n) _Pragma("unroll") for (int k = 0; k < 2; ++k) dst[n][k] = *(const LAS bf16x8*)(lds + PG8_SB(b, h) + boff + n * 2048 + k * 1024); } while (0)
; #define PG8_MMA(ai, bj, At, Bt) do { __builtin_amdgcn_s_setprio(1); _Pragma("unroll") for (int m = 0; m < 4; ++m) _Pragma("unroll") for (int n = 0; n < 2; ++n) _Pragma("unroll") for (int k = 0; k < 2; ++k) \
;         acc[ai][bj][m][n] = __builtin_amdgcn_mfma_f32_16x16x32_bf16(Bt[n][k], At[m][k], acc[ai][bj][m][n], 0, 0, 0); __builtin_amdgcn_s_setprio(0); } while (0)
; #define PG8_WAIT_V(n) asm volatile("s_waitcnt vmcnt(" #n ")" ::: "memory")
; #define PG8_WAIT_L(n) asm volatile("s_waitcnt lgkmcnt(" #n ")" ::: "memory")
; #define PG8_BAR __builtin_amdgcn_s_barrier()
; #define PG8_SCHED __builtin_amdgcn_sched_barrier(0)
; template <class Epi, class Sched>
; __device__ __forceinline__ void gemm_phase(LAS unsigned char* lds, const Gemm g, const Sched& S, const Epi& E, int tid) {
;     ...
;             PG8_WAIT_L(8); PG8_BAR; PG8_WAIT_L(0); PG8_MMA(0, 0, At, B0); PG8_BAR; PG8_SCHED;
;             PG8_LDB(B1, 1, 1); PG8_STAGE(PG8_SB(1, 0), b3, voffB);
;             PG8_BAR; PG8_WAIT_L(0); PG8_MMA(0, 1, At, B1); PG8_BAR;
;             PG8_LDA(At, 1, 1); PG8_STAGE(PG8_SA(1, 0), a3, voffA);
;             PG8_BAR; PG8_WAIT_L(0); PG8_MMA(1, 0, At, B0); PG8_BAR; PG8_SCHED;
;             PG8_STAGE(PG8_SB(1, 1), b3 + hstep, voffB);
;             PG8_WAIT_V(6); PG8_BAR; PG8_MMA(1, 1, At, B1); PG8_BAR;
	s_waitcnt lgkmcnt(0)
	v_mfma_f32_16x16x32_bf16 v[124:127], v[144:147], v[168:171], v[124:127]
	ds_read_b128 v[184:187], v143 offset:33792
	v_mfma_f32_16x16x32_bf16 v[120:123], v[160:163], v[168:171], v[120:123]
	ds_read_b128 v[192:195], v143 offset:35840
	v_mfma_f32_16x16x32_bf16 v[116:119], v[144:147], v[188:191], v[116:119]
	ds_read_b128 v[200:203], v143 offset:37888
	v_mfma_f32_16x16x32_bf16 v[112:115], v[160:163], v[188:191], v[112:115]
	ds_read_b128 v[208:211], v143 offset:39936
	v_mfma_f32_16x16x32_bf16 v[100:103], v[144:147], v[196:199], v[100:103]
	v_mfma_f32_16x16x32_bf16 v[96:99], v[160:163], v[196:199], v[96:99]
	v_mfma_f32_16x16x32_bf16 v[84:87], v[144:147], v[204:207], v[84:87]
	v_mfma_f32_16x16x32_bf16 v[80:83], v[160:163], v[204:207], v[80:83]
	s_waitcnt lgkmcnt(0)
	v_mfma_f32_16x16x32_bf16 v[124:127], v[148:151], v[184:187], v[124:127]
	v_mfma_f32_16x16x32_bf16 v[120:123], v[164:167], v[184:187], v[120:123]
	v_mfma_f32_16x16x32_bf16 v[116:119], v[148:151], v[192:195], v[116:119]
	v_mfma_f32_16x16x32_bf16 v[112:115], v[164:167], v[192:195], v[112:115]
	v_mfma_f32_16x16x32_bf16 v[100:103], v[148:151], v[200:203], v[100:103]
	v_mfma_f32_16x16x32_bf16 v[96:99], v[164:167], v[200:203], v[96:99]
	v_mfma_f32_16x16x32_bf16 v[84:87], v[148:151], v[208:211], v[84:87]
	v_mfma_f32_16x16x32_bf16 v[80:83], v[164:167], v[208:211], v[80:83]
	s_barrier
	s_setprio 0
	v_lshl_add_u64 v[238:239], s[34:35], 0, v[130:131]
	s_mov_b32 m0, s91
	s_nop 0
	global_load_lds_dwordx4 v[238:239], off
	s_add_i32 s17, 0, 0x1c000
	s_add_i32 s1, s1, s85
	v_add_u32_e32 v183, s17, v141
	v_lshl_add_u64 v[152:153], v[152:153], 0, s[8:9]
	s_mov_b32 m0, s1
	ds_read_b128 v[212:215], v183
	ds_read_b128 v[216:219], v183 offset:1024
	ds_read_b128 v[220:223], v183 offset:2048
	ds_read_b128 v[224:227], v183 offset:3072
	global_load_lds_dwordx4 v[152:153], off
	v_lshl_add_u64 v[152:153], v[228:229], 0, s[8:9]
	s_add_i32 m0, s1, 0x2000
	s_nop 0
	global_load_lds_dwordx4 v[152:153], off
	s_setprio 1
	s_barrier
	s_waitcnt lgkmcnt(0)
	v_mfma_f32_16x16x32_bf16 v[108:111], v[212:215], v[168:171], v[108:111]
	v_mfma_f32_16x16x32_bf16 v[104:107], v[220:223], v[168:171], v[104:107]
	v_mfma_f32_16x16x32_bf16 v[92:95], v[212:215], v[188:191], v[92:95]
	v_mfma_f32_16x16x32_bf16 v[88:91], v[220:223], v[188:191], v[88:91]
	v_mfma_f32_16x16x32_bf16 v[76:79], v[212:215], v[196:199], v[76:79]
	v_mfma_f32_16x16x32_bf16 v[72:75], v[220:223], v[196:199], v[72:75]
	s_mov_b32 m0, s92
	v_mfma_f32_16x16x32_bf16 v[68:71], v[212:215], v[204:207], v[68:71]
	v_lshl_add_u64 v[152:153], v[230:231], 0, s[8:9]
	v_mfma_f32_16x16x32_bf16 v[64:67], v[220:223], v[204:207], v[64:67]
	v_mfma_f32_16x16x32_bf16 v[108:111], v[216:219], v[184:187], v[108:111]
	v_mfma_f32_16x16x32_bf16 v[104:107], v[224:227], v[184:187], v[104:107]
	v_mfma_f32_16x16x32_bf16 v[92:95], v[216:219], v[192:195], v[92:95]
	v_mfma_f32_16x16x32_bf16 v[88:91], v[224:227], v[192:195], v[88:91]
	v_mfma_f32_16x16x32_bf16 v[76:79], v[216:219], v[200:203], v[76:79]
	v_mfma_f32_16x16x32_bf16 v[72:75], v[224:227], v[200:203], v[72:75]
	v_mfma_f32_16x16x32_bf16 v[68:71], v[216:219], v[208:211], v[68:71]
	v_mfma_f32_16x16x32_bf16 v[64:67], v[224:227], v[208:211], v[64:67]
	s_barrier
	s_setprio 0
	ds_read_b128 v[168:171], v143 offset:49152
	ds_read_b128 v[184:187], v143 offset:50176
	ds_read_b128 v[188:191], v143 offset:51200
	ds_read_b128 v[192:195], v143 offset:52224
	ds_read_b128 v[196:199], v143 offset:53248
	ds_read_b128 v[200:203], v143 offset:54272
	ds_read_b128 v[204:207], v143 offset:55296
	ds_read_b128 v[208:211], v143 offset:56320
	global_load_lds_dwordx4 v[152:153], off
	v_lshl_add_u64 v[152:153], v[232:233], 0, s[8:9]
	s_mov_b32 m0, s93
	s_nop 0
	global_load_lds_dwordx4 v[152:153], off
	s_setprio 1
	s_barrier
	s_waitcnt lgkmcnt(0)
	v_mfma_f32_16x16x32_bf16 v[60:63], v[144:147], v[168:171], v[60:63]
	v_mfma_f32_16x16x32_bf16 v[56:59], v[160:163], v[168:171], v[56:59]
	v_mfma_f32_16x16x32_bf16 v[52:55], v[144:147], v[188:191], v[52:55]
	v_mfma_f32_16x16x32_bf16 v[48:51], v[160:163], v[188:191], v[48:51]
	v_mfma_f32_16x16x32_bf16 v[36:39], v[144:147], v[196:199], v[36:39]
	v_mfma_f32_16x16x32_bf16 v[32:35], v[160:163], v[196:199], v[32:35]
	v_mfma_f32_16x16x32_bf16 v[20:23], v[144:147], v[204:207], v[20:23]
	v_mfma_f32_16x16x32_bf16 v[16:19], v[160:163], v[204:207], v[16:19]
	v_mfma_f32_16x16x32_bf16 v[60:63], v[148:151], v[184:187], v[60:63]
	v_mfma_f32_16x16x32_bf16 v[56:59], v[164:167], v[184:187], v[56:59]
	v_mfma_f32_16x16x32_bf16 v[52:55], v[148:151], v[192:195], v[52:55]
	v_mfma_f32_16x16x32_bf16 v[48:51], v[164:167], v[192:195], v[48:51]
	v_mfma_f32_16x16x32_bf16 v[36:39], v[148:151], v[200:203], v[36:39]
	v_mfma_f32_16x16x32_bf16 v[32:35], v[164:167], v[200:203], v[32:35]
	v_mfma_f32_16x16x32_bf16 v[20:23], v[148:151], v[208:211], v[20:23]
	v_mfma_f32_16x16x32_bf16 v[16:19], v[164:167], v[208:211], v[16:19]
	s_barrier
	s_setprio 0
	s_add_i32 s1, s17, s85
	v_lshl_add_u64 v[144:145], v[234:235], 0, s[8:9]
	s_mov_b32 m0, s1
	s_nop 0
	global_load_lds_dwordx4 v[144:145], off
	v_lshl_add_u64 v[144:145], v[236:237], 0, s[8:9]
	s_add_i32 m0, s1, 0x2000
	s_nop 0
	global_load_lds_dwordx4 v[144:145], off
	s_waitcnt vmcnt(6)
	s_setprio 1
	s_barrier
	v_mfma_f32_16x16x32_bf16 v[44:47], v[212:215], v[168:171], v[44:47]
	v_mfma_f32_16x16x32_bf16 v[40:43], v[220:223], v[168:171], v[40:43]
	v_mfma_f32_16x16x32_bf16 v[28:31], v[212:215], v[188:191], v[28:31]
	v_mfma_f32_16x16x32_bf16 v[24:27], v[220:223], v[188:191], v[24:27]
	v_mfma_f32_16x16x32_bf16 v[12:15], v[212:215], v[196:199], v[12:15]
	v_mfma_f32_16x16x32_bf16 v[8:11], v[220:223], v[196:199], v[8:11]
	s_add_u32 vcc_lo, vcc_lo, 0x100
	v_mfma_f32_16x16x32_bf16 v[4:7], v[212:215], v[204:207], v[4:7]
	s_addc_u32 vcc_hi, vcc_hi, 0
	v_mfma_f32_16x16x32_bf16 v[0:3], v[220:223], v[204:207], v[0:3]
	s_add_u32 s96, s96, 0x100
	v_mfma_f32_16x16x32_bf16 v[44:47], v[216:219], v[184:187], v[44:47]
	s_addc_u32 s65, s65, 0
	v_mfma_f32_16x16x32_bf16 v[40:43], v[224:227], v[184:187], v[40:43]
	s_cmp_ge_u32 s0, s94
	v_mfma_f32_16x16x32_bf16 v[28:31], v[216:219], v[192:195], v[28:31]
	s_mov_b32 s34, s0
	v_mfma_f32_16x16x32_bf16 v[24:27], v[224:227], v[192:195], v[24:27]
	v_mfma_f32_16x16x32_bf16 v[12:15], v[216:219], v[200:203], v[12:15]
	v_mfma_f32_16x16x32_bf16 v[8:11], v[224:227], v[200:203], v[8:11]
	v_mfma_f32_16x16x32_bf16 v[4:7], v[216:219], v[208:211], v[4:7]
	v_mfma_f32_16x16x32_bf16 v[0:3], v[224:227], v[208:211], v[0:3]
	s_barrier
	s_setprio 0
	s_cbranch_scc0 .LBB0_100

; #define PG8_STAGE(bufoff, gbase, voff) do { _Pragma("unroll") for (int _i = 0; _i < 2; ++_i) \
;         __builtin_amdgcn_global_load_lds((const unsigned*)((const char*)(gbase) + (voff)[_i]), (LAS unsigned*)(lds + (bufoff) + ldsw + _i * 8192), 16, 0, 0); } while (0)
; #define PG8_LDA(dst, b, h) do { _Pragma("unroll") for (int m = 0; m < 4; ++m) _Pragma("unroll") for (int k = 0; k < 2; ++k) dst[m][k] = *(const LAS bf16x8*)(lds + PG8_SA(b, h) + aoff + m * 2048 + k * 1024); } while (0)
; #define PG8_LDB(dst, b, h) do { _Pragma("unroll") for (int n = 0; n < 2; ++n) _Pragma("unroll") for (int k = 0; k < 2; ++k) dst[n][k] = *(const LAS bf16x8*)(lds + PG8_SB(b, h) + boff + n * 2048 + k * 1024); } while (0)
; #define PG8_MMA(ai, bj, At, Bt) do { __builtin_amdgcn_s_setprio(1); _Pragma("unroll") for (int m = 0; m < 4; ++m) _Pragma("unroll") for (int n = 0; n < 2; ++n) _Pragma("unroll") for (int k = 0; k < 2; ++k) \
;         acc[ai][bj][m][n] = __builtin_amdgcn_mfma_f32_16x16x32_bf16(Bt[n][k], At[m][k], acc[ai][bj][m][n], 0, 0, 0); __builtin_amdgcn_s_setprio(0); } while (0)
; #define PG8_WAIT_L(n) asm volatile("s_waitcnt lgkmcnt(" #n ")" ::: "memory")
; template <class Epi, class Sched>
; __device__ __forceinline__ void gemm_phase(LAS unsigned char* lds, const Gemm g, const Sched& S, const Epi& E, int tid) {
;     ...
;         const bool has_next = S.next(ui + 1, nxt);
;         const char* nA = has_next ? (const char*)g.A + (size_t)nxt.pm * tstep : cA; const char* nB = has_next ? (const char*)g.Bt + (size_t)nxt.pn * tstep : cB;
;         for (int t = 0; t < nt; t += 2) {
;             const bool last = (t == nt - 2);
;             const char* a1 = cA + (size_t)(t + 1) * kstep;
;             const char* a2 = last ? nA : cA + (size_t)(t + 2) * kstep; const char* b2 = last ? nB : cB + (size_t)(t + 2) * kstep;
;             const char* a3 = a2 + kstep; const char* b3 = b2 + kstep;
;             PG8_LDB(B0, 0, 0); PG8_SCHED; PG8_LDA(At, 0, 0); PG8_STAGE(PG8_SA(1, 1), a1 + hstep, voffA);
;             PG8_WAIT_L(8); PG8_BAR; PG8_WAIT_L(0); PG8_MMA(0, 0, At, B0); PG8_BAR; PG8_SCHED;
;             PG8_LDB(B1, 0, 1); PG8_STAGE(PG8_SB(0, 0), b2, voffB);
;             PG8_BAR; PG8_WAIT_L(0); PG8_MMA(0, 1, At, B1); PG8_BAR;
;             PG8_LDA(At, 0, 1); PG8_STAGE(PG8_SA(0, 0), a2, voffA);
;             PG8_BAR; PG8_WAIT_L(0); PG8_MMA(1, 0, At, B0); PG8_BAR; PG8_SCHED;
.LBB0_114:
	s_ashr_i32 s25, s24, 31
	s_lshl_b64 s[0:1], s[24:25], 19
	v_cmp_lt_i64_e32 vcc, s[28:29], v[158:159]
	s_add_u32 s28, s26, s0
	s_addc_u32 s29, s27, s1
	s_and_b64 s[0:1], vcc, exec
	s_cselect_b32 s25, s29, s41
	s_cselect_b32 s53, s28, s40
	s_ashr_i32 s15, s14, 31
	s_lshl_b64 s[0:1], s[14:15], 19
	s_add_u32 s30, s19, s0
	s_addc_u32 s31, s44, s1
	s_and_b64 s[0:1], vcc, exec
	s_cselect_b32 s15, s31, s43
	s_cselect_b32 s55, s30, s42
	s_add_u32 s40, s40, 0x40080
	s_addc_u32 s41, s41, 0
	s_add_u32 s58, s42, 0x100
	s_addc_u32 s60, s43, 0
	s_mov_b32 s61, -2
	v_add_u32_e32 v240, 0x10000, v143
	ds_read_b128 v[138:141], v240
	ds_read_b128 v[146:149], v240 offset:1024
	ds_read_b128 v[150:153], v240 offset:2048
	ds_read_b128 v[160:163], v240 offset:3072
	v_lshl_add_u64 v[208:209], s[40:41], 0, v[134:135]
	s_add_i32 m0, s39, 0xc000
	ds_read_b128 v[164:167], v145
	ds_read_b128 v[184:187], v145 offset:2048
	ds_read_b128 v[192:195], v145 offset:4096
	ds_read_b128 v[200:203], v145 offset:6144
	global_load_lds_dwordx4 v[208:209], off
	s_add_u32 s0, s40, 0xfffc0080
	s_addc_u32 s1, s41, -1
	s_add_i32 s17, 0, 0x10000
	s_cmp_eq_u32 s61, 12
	s_cselect_b32 s43, s25, s1
	s_cselect_b32 s42, s53, s0
	s_cselect_b32 s35, s15, s60
	s_cselect_b32 s34, s55, s58
	s_waitcnt lgkmcnt(4)
	s_setprio 1
	s_barrier
	s_waitcnt lgkmcnt(0)
	v_mfma_f32_16x16x32_bf16 v[124:127], v[138:141], v[164:167], 0
	ds_read_b128 v[168:171], v145 offset:1024
	v_mfma_f32_16x16x32_bf16 v[120:123], v[150:153], v[164:167], 0
	ds_read_b128 v[188:191], v145 offset:3072
	v_mfma_f32_16x16x32_bf16 v[108:111], v[138:141], v[184:187], 0
	ds_read_b128 v[196:199], v145 offset:5120
	v_mfma_f32_16x16x32_bf16 v[104:107], v[150:153], v[184:187], 0
	ds_read_b128 v[204:207], v145 offset:7168
	v_mfma_f32_16x16x32_bf16 v[92:95], v[138:141], v[192:195], 0
	v_mfma_f32_16x16x32_bf16 v[88:91], v[150:153], v[192:195], 0
	v_mfma_f32_16x16x32_bf16 v[76:79], v[138:141], v[200:203], 0
	v_mfma_f32_16x16x32_bf16 v[72:75], v[150:153], v[200:203], 0
	s_waitcnt lgkmcnt(0)
	v_mfma_f32_16x16x32_bf16 v[124:127], v[146:149], v[168:171], v[124:127]
	v_mfma_f32_16x16x32_bf16 v[120:123], v[160:163], v[168:171], v[120:123]
	v_mfma_f32_16x16x32_bf16 v[108:111], v[146:149], v[188:191], v[108:111]
	v_mfma_f32_16x16x32_bf16 v[104:107], v[160:163], v[188:191], v[104:107]
	v_mfma_f32_16x16x32_bf16 v[92:95], v[146:149], v[196:199], v[92:95]
	v_mfma_f32_16x16x32_bf16 v[88:91], v[160:163], v[196:199], v[88:91]
	v_mfma_f32_16x16x32_bf16 v[76:79], v[146:149], v[204:207], v[76:79]
	v_mfma_f32_16x16x32_bf16 v[72:75], v[160:163], v[204:207], v[72:75]
	s_barrier
	s_setprio 0
	v_lshl_add_u64 v[238:239], s[40:41], 0, v[136:137]
	s_add_i32 m0, s39, 0xe000
	s_nop 0
	global_load_lds_dwordx4 v[238:239], off
	s_add_i32 s63, 0, 0x14000
	s_add_i32 s0, s17, s45
	v_add_u32_e32 v183, s63, v143
	v_lshl_add_u64 v[224:225], s[34:35], 0, v[154:155]
	s_mov_b32 m0, s0
	ds_read_b128 v[208:211], v183
	ds_read_b128 v[212:215], v183 offset:1024
	ds_read_b128 v[216:219], v183 offset:2048
	ds_read_b128 v[220:223], v183 offset:3072
	global_load_lds_dwordx4 v[224:225], off
	v_lshl_add_u64 v[226:227], s[34:35], 0, v[128:129]
	s_add_i32 m0, s0, 0x2000
	s_nop 0
	global_load_lds_dwordx4 v[226:227], off
	s_setprio 1
	s_barrier
	s_waitcnt lgkmcnt(0)
	v_mfma_f32_16x16x32_bf16 v[116:119], v[208:211], v[164:167], 0
	v_mfma_f32_16x16x32_bf16 v[112:115], v[216:219], v[164:167], 0
	v_mfma_f32_16x16x32_bf16 v[100:103], v[208:211], v[184:187], 0
	v_mfma_f32_16x16x32_bf16 v[96:99], v[216:219], v[184:187], 0
	v_mfma_f32_16x16x32_bf16 v[84:87], v[208:211], v[192:195], 0
	v_mfma_f32_16x16x32_bf16 v[80:83], v[216:219], v[192:195], 0
	s_mov_b32 m0, s39
	v_mfma_f32_16x16x32_bf16 v[68:71], v[208:211], v[200:203], 0
	v_lshl_add_u64 v[228:229], s[42:43], 0, v[132:133]
	v_mfma_f32_16x16x32_bf16 v[64:67], v[216:219], v[200:203], 0
	v_mfma_f32_16x16x32_bf16 v[116:119], v[212:215], v[168:171], v[116:119]
	v_mfma_f32_16x16x32_bf16 v[112:115], v[220:223], v[168:171], v[112:115]
	v_mfma_f32_16x16x32_bf16 v[100:103], v[212:215], v[188:191], v[100:103]
	v_mfma_f32_16x16x32_bf16 v[96:99], v[220:223], v[188:191], v[96:99]
	v_mfma_f32_16x16x32_bf16 v[84:87], v[212:215], v[196:199], v[84:87]
	v_mfma_f32_16x16x32_bf16 v[80:83], v[220:223], v[196:199], v[80:83]
	v_mfma_f32_16x16x32_bf16 v[68:71], v[212:215], v[204:207], v[68:71]
	v_mfma_f32_16x16x32_bf16 v[64:67], v[220:223], v[204:207], v[64:67]
	s_barrier
	s_setprio 0
	ds_read_b128 v[164:167], v145 offset:16384
	ds_read_b128 v[168:171], v145 offset:17408
	ds_read_b128 v[184:187], v145 offset:18432
	ds_read_b128 v[188:191], v145 offset:19456
	ds_read_b128 v[192:195], v145 offset:20480
	ds_read_b128 v[196:199], v145 offset:21504
	ds_read_b128 v[200:203], v145 offset:22528
	ds_read_b128 v[204:207], v145 offset:23552
	global_load_lds_dwordx4 v[228:229], off
	v_lshl_add_u64 v[230:231], s[42:43], 0, v[130:131]
	s_mov_b32 m0, s47
	s_nop 0
	global_load_lds_dwordx4 v[230:231], off
	s_setprio 1
	s_barrier
	s_waitcnt lgkmcnt(0)
	v_mfma_f32_16x16x32_bf16 v[60:63], v[138:141], v[164:167], 0
	v_mfma_f32_16x16x32_bf16 v[56:59], v[150:153], v[164:167], 0
	v_mfma_f32_16x16x32_bf16 v[44:47], v[138:141], v[184:187], 0
	v_mfma_f32_16x16x32_bf16 v[40:43], v[150:153], v[184:187], 0
	v_mfma_f32_16x16x32_bf16 v[28:31], v[138:141], v[192:195], 0
	v_mfma_f32_16x16x32_bf16 v[24:27], v[150:153], v[192:195], 0
	v_mfma_f32_16x16x32_bf16 v[12:15], v[138:141], v[200:203], 0
	v_mfma_f32_16x16x32_bf16 v[8:11], v[150:153], v[200:203], 0
	v_mfma_f32_16x16x32_bf16 v[60:63], v[146:149], v[168:171], v[60:63]
	v_mfma_f32_16x16x32_bf16 v[56:59], v[160:163], v[168:171], v[56:59]
	v_mfma_f32_16x16x32_bf16 v[44:47], v[146:149], v[188:191], v[44:47]
	v_mfma_f32_16x16x32_bf16 v[40:43], v[160:163], v[188:191], v[40:43]
	v_mfma_f32_16x16x32_bf16 v[28:31], v[146:149], v[196:199], v[28:31]
	v_mfma_f32_16x16x32_bf16 v[24:27], v[160:163], v[196:199], v[24:27]
	v_mfma_f32_16x16x32_bf16 v[12:15], v[146:149], v[204:207], v[12:15]
	v_mfma_f32_16x16x32_bf16 v[8:11], v[160:163], v[204:207], v[8:11]
	s_barrier
; #define PG8_STAGE(bufoff, gbase, voff) do { _Pragma("unroll") for (int _i = 0; _i < 2; ++_i) \
;         __builtin_amdgcn_global_load_lds((const unsigned*)((const char*)(gbase) + (voff)[_i]), (LAS unsigned*)(lds + (bufoff) + ldsw + _i * 8192), 16, 0, 0); } while (0)
; #define PG8_LDA(dst, b, h) do { _Pragma("unroll") for (int m = 0; m < 4; ++m) _Pragma("unroll") for (int k = 0; k < 2; ++k) dst[m][k] = *(const LAS bf16x8*)(lds + PG8_SA(b, h) + aoff + m * 2048 + k * 1024); } while (0)
; #define PG8_LDB(dst, b, h) do { _Pragma("unroll") for (int n = 0; n < 2; ++n) _Pragma("unroll") for (int k = 0; k < 2; ++k) dst[n][k] = *(const LAS bf16x8*)(lds + PG8_SB(b, h) + boff + n * 2048 + k * 1024); } while (0)
; #define PG8_MMA(ai, bj, At, Bt) do { __builtin_amdgcn_s_setprio(1); _Pragma("unroll") for (int m = 0; m < 4; ++m) _Pragma("unroll") for (int n = 0; n < 2; ++n) _Pragma("unroll") for (int k = 0; k < 2; ++k) \
;         acc[ai][bj][m][n] = __builtin_amdgcn_mfma_f32_16x16x32_bf16(Bt[n][k], At[m][k], acc[ai][bj][m][n], 0, 0, 0); __builtin_amdgcn_s_setprio(0); } while (0)
; #define PG8_WAIT_V(n) asm volatile("s_waitcnt vmcnt(" #n ")" ::: "memory")
; #define PG8_WAIT_L(n) asm volatile("s_waitcnt lgkmcnt(" #n ")" ::: "memory")
; #define PG8_BAR __builtin_amdgcn_s_barrier()
; #define PG8_SCHED __builtin_amdgcn_sched_barrier(0)
; template <class Epi, class Sched>
; __device__ __forceinline__ void gemm_phase(LAS unsigned char* lds, const Gemm g, const Sched& S, const Epi& E, int tid) {
;     ...
;             PG8_STAGE(PG8_SB(0, 1), b2 + hstep, voffB);
;             PG8_WAIT_V(6); PG8_BAR; PG8_MMA(1, 1, At, B1); PG8_BAR;
;             PG8_LDB(B0, 1, 0); PG8_SCHED; PG8_LDA(At, 1, 0); PG8_STAGE(PG8_SA(0, 1), a2 + hstep, voffA);
;             PG8_WAIT_L(8); PG8_BAR; PG8_WAIT_L(0); PG8_MMA(0, 0, At, B0); PG8_BAR; PG8_SCHED;
;             PG8_LDB(B1, 1, 1); PG8_STAGE(PG8_SB(1, 0), b3, voffB);
;             PG8_BAR; PG8_WAIT_L(0); PG8_MMA(0, 1, At, B1); PG8_BAR;
;             PG8_LDA(At, 1, 1); PG8_STAGE(PG8_SA(1, 0), a3, voffA);
;             PG8_BAR; PG8_WAIT_L(0); PG8_MMA(1, 0, At, B0); PG8_BAR; PG8_SCHED;
	s_setprio 0
	s_add_u32 s0, s34, 0x40000
	s_addc_u32 s1, s35, 0
	s_add_i32 s17, s63, s45
	v_lshl_add_u64 v[138:139], s[0:1], 0, v[154:155]
	s_mov_b32 m0, s17
	s_nop 0
	global_load_lds_dwordx4 v[138:139], off
	v_lshl_add_u64 v[138:139], s[0:1], 0, v[128:129]
	s_add_i32 m0, s17, 0x2000
	s_nop 0
	global_load_lds_dwordx4 v[138:139], off
	s_waitcnt vmcnt(16)
	s_setprio 1
	s_barrier
	v_mfma_f32_16x16x32_bf16 v[52:55], v[208:211], v[164:167], 0
	v_mfma_f32_16x16x32_bf16 v[48:51], v[216:219], v[164:167], 0
	v_mfma_f32_16x16x32_bf16 v[36:39], v[208:211], v[184:187], 0
	v_mfma_f32_16x16x32_bf16 v[32:35], v[216:219], v[184:187], 0
	v_mfma_f32_16x16x32_bf16 v[20:23], v[208:211], v[192:195], 0
	v_mfma_f32_16x16x32_bf16 v[16:19], v[216:219], v[192:195], 0
	s_add_i32 s17, 0, 0x18000
	v_mfma_f32_16x16x32_bf16 v[4:7], v[208:211], v[200:203], 0
	v_add_u32_e32 v160, s17, v143
	v_mfma_f32_16x16x32_bf16 v[0:3], v[216:219], v[200:203], 0
	v_mfma_f32_16x16x32_bf16 v[52:55], v[212:215], v[168:171], v[52:55]
	v_mfma_f32_16x16x32_bf16 v[48:51], v[220:223], v[168:171], v[48:51]
	v_mfma_f32_16x16x32_bf16 v[36:39], v[212:215], v[188:191], v[36:39]
	v_mfma_f32_16x16x32_bf16 v[32:35], v[220:223], v[188:191], v[32:35]
	v_mfma_f32_16x16x32_bf16 v[20:23], v[212:215], v[196:199], v[20:23]
	v_mfma_f32_16x16x32_bf16 v[16:19], v[220:223], v[196:199], v[16:19]
	v_mfma_f32_16x16x32_bf16 v[4:7], v[212:215], v[204:207], v[4:7]
	v_mfma_f32_16x16x32_bf16 v[0:3], v[220:223], v[204:207], v[0:3]
	s_barrier
	s_setprio 0
	ds_read_b128 v[138:141], v160
	ds_read_b128 v[146:149], v160 offset:1024
	ds_read_b128 v[150:153], v160 offset:2048
	ds_read_b128 v[160:163], v160 offset:3072
	s_add_u32 s0, s42, 0x40000
	s_addc_u32 s1, s43, 0
	s_mov_b32 m0, s48
	v_lshl_add_u64 v[208:209], s[0:1], 0, v[132:133]
	ds_read_b128 v[164:167], v145 offset:32768
	ds_read_b128 v[184:187], v145 offset:34816
	ds_read_b128 v[192:195], v145 offset:36864
	ds_read_b128 v[200:203], v145 offset:38912
	global_load_lds_dwordx4 v[208:209], off
	s_waitcnt lgkmcnt(4)
	s_setprio 1
	s_barrier
	s_waitcnt lgkmcnt(0)
	v_mfma_f32_16x16x32_bf16 v[124:127], v[138:141], v[164:167], v[124:127]
	ds_read_b128 v[168:171], v145 offset:33792
	v_mfma_f32_16x16x32_bf16 v[120:123], v[150:153], v[164:167], v[120:123]
	ds_read_b128 v[188:191], v145 offset:35840
	v_mfma_f32_16x16x32_bf16 v[108:111], v[138:141], v[184:187], v[108:111]
	ds_read_b128 v[196:199], v145 offset:37888
	v_mfma_f32_16x16x32_bf16 v[104:107], v[150:153], v[184:187], v[104:107]
	ds_read_b128 v[204:207], v145 offset:39936
	v_mfma_f32_16x16x32_bf16 v[92:95], v[138:141], v[192:195], v[92:95]
	v_mfma_f32_16x16x32_bf16 v[88:91], v[150:153], v[192:195], v[88:91]
	v_mfma_f32_16x16x32_bf16 v[76:79], v[138:141], v[200:203], v[76:79]
	v_mfma_f32_16x16x32_bf16 v[72:75], v[150:153], v[200:203], v[72:75]
	s_waitcnt lgkmcnt(0)
	v_mfma_f32_16x16x32_bf16 v[124:127], v[146:149], v[168:171], v[124:127]
	v_mfma_f32_16x16x32_bf16 v[120:123], v[160:163], v[168:171], v[120:123]
	v_mfma_f32_16x16x32_bf16 v[108:111], v[146:149], v[188:191], v[108:111]
	v_mfma_f32_16x16x32_bf16 v[104:107], v[160:163], v[188:191], v[104:107]
	v_mfma_f32_16x16x32_bf16 v[92:95], v[146:149], v[196:199], v[92:95]
	v_mfma_f32_16x16x32_bf16 v[88:91], v[160:163], v[196:199], v[88:91]
	v_mfma_f32_16x16x32_bf16 v[76:79], v[146:149], v[204:207], v[76:79]
	v_mfma_f32_16x16x32_bf16 v[72:75], v[160:163], v[204:207], v[72:75]
	s_barrier
	s_setprio 0
	v_lshl_add_u64 v[238:239], s[0:1], 0, v[130:131]
	s_mov_b32 m0, s49
	s_nop 0
	global_load_lds_dwordx4 v[238:239], off
	s_add_i32 s42, 0, 0x1c000
	s_add_i32 s0, s17, s45
	v_add_u32_e32 v183, s42, v143
	v_lshl_add_u64 v[224:225], v[224:225], 0, s[8:9]
	s_mov_b32 m0, s0
	ds_read_b128 v[208:211], v183
	ds_read_b128 v[212:215], v183 offset:1024
	ds_read_b128 v[216:219], v183 offset:2048
	ds_read_b128 v[220:223], v183 offset:3072
	global_load_lds_dwordx4 v[224:225], off
	v_lshl_add_u64 v[224:225], v[226:227], 0, s[8:9]
	s_add_i32 m0, s0, 0x2000
	s_nop 0
	global_load_lds_dwordx4 v[224:225], off
	s_waitcnt vmcnt(10)
	s_setprio 1
	s_barrier
	s_waitcnt lgkmcnt(0)
	v_mfma_f32_16x16x32_bf16 v[116:119], v[208:211], v[164:167], v[116:119]
	v_mfma_f32_16x16x32_bf16 v[112:115], v[216:219], v[164:167], v[112:115]
	v_mfma_f32_16x16x32_bf16 v[100:103], v[208:211], v[184:187], v[100:103]
	v_mfma_f32_16x16x32_bf16 v[96:99], v[216:219], v[184:187], v[96:99]
	v_mfma_f32_16x16x32_bf16 v[84:87], v[208:211], v[192:195], v[84:87]
	v_mfma_f32_16x16x32_bf16 v[80:83], v[216:219], v[192:195], v[80:83]
	s_mov_b32 m0, s6
	v_mfma_f32_16x16x32_bf16 v[68:71], v[208:211], v[200:203], v[68:71]
	v_lshl_add_u64 v[224:225], v[228:229], 0, s[8:9]
	v_mfma_f32_16x16x32_bf16 v[64:67], v[216:219], v[200:203], v[64:67]
	v_mfma_f32_16x16x32_bf16 v[116:119], v[212:215], v[168:171], v[116:119]
	v_mfma_f32_16x16x32_bf16 v[112:115], v[220:223], v[168:171], v[112:115]
	v_mfma_f32_16x16x32_bf16 v[100:103], v[212:215], v[188:191], v[100:103]
	v_mfma_f32_16x16x32_bf16 v[96:99], v[220:223], v[188:191], v[96:99]
	v_mfma_f32_16x16x32_bf16 v[84:87], v[212:215], v[196:199], v[84:87]
	v_mfma_f32_16x16x32_bf16 v[80:83], v[220:223], v[196:199], v[80:83]
	v_mfma_f32_16x16x32_bf16 v[68:71], v[212:215], v[204:207], v[68:71]
	v_mfma_f32_16x16x32_bf16 v[64:67], v[220:223], v[204:207], v[64:67]
	s_barrier
	s_setprio 0
	ds_read_b128 v[164:167], v145 offset:49152
	ds_read_b128 v[168:171], v145 offset:50176
	ds_read_b128 v[184:187], v145 offset:51200
	ds_read_b128 v[188:191], v145 offset:52224
	ds_read_b128 v[192:195], v145 offset:53248
	ds_read_b128 v[196:199], v145 offset:54272
	ds_read_b128 v[200:203], v145 offset:55296
	ds_read_b128 v[204:207], v145 offset:56320
	global_load_lds_dwordx4 v[224:225], off
	v_lshl_add_u64 v[224:225], v[230:231], 0, s[8:9]
	s_mov_b32 m0, s50
	s_nop 0
	global_load_lds_dwordx4 v[224:225], off
	s_setprio 1
	s_barrier
; #define PG8_STAGE(bufoff, gbase, voff) do { _Pragma("unroll") for (int _i = 0; _i < 2; ++_i) \
;         __builtin_amdgcn_global_load_lds((const unsigned*)((const char*)(gbase) + (voff)[_i]), (LAS unsigned*)(lds + (bufoff) + ldsw + _i * 8192), 16, 0, 0); } while (0)
; #define PG8_LDA(dst, b, h) do { _Pragma("unroll") for (int m = 0; m < 4; ++m) _Pragma("unroll") for (int k = 0; k < 2; ++k) dst[m][k] = *(const LAS bf16x8*)(lds + PG8_SA(b, h) + aoff + m * 2048 + k * 1024); } while (0)
; #define PG8_LDB(dst, b, h) do { _Pragma("unroll") for (int n = 0; n < 2; ++n) _Pragma("unroll") for (int k = 0; k < 2; ++k) dst[n][k] = *(const LAS bf16x8*)(lds + PG8_SB(b, h) + boff + n * 2048 + k * 1024); } while (0)
; #define PG8_MMA(ai, bj, At, Bt) do { __builtin_amdgcn_s_setprio(1); _Pragma("unroll") for (int m = 0; m < 4; ++m) _Pragma("unroll") for (int n = 0; n < 2; ++n) _Pragma("unroll") for (int k = 0; k < 2; ++k) \
;         acc[ai][bj][m][n] = __builtin_amdgcn_mfma_f32_16x16x32_bf16(Bt[n][k], At[m][k], acc[ai][bj][m][n], 0, 0, 0); __builtin_amdgcn_s_setprio(0); } while (0)
; #define PG8_WAIT_V(n) asm volatile("s_waitcnt vmcnt(" #n ")" ::: "memory")
; #define PG8_WAIT_L(n) asm volatile("s_waitcnt lgkmcnt(" #n ")" ::: "memory")
; #define PG8_BAR __builtin_amdgcn_s_barrier()
; #define PG8_SCHED __builtin_amdgcn_sched_barrier(0)
; template <class Epi, class Sched>
; __device__ __forceinline__ void gemm_phase(LAS unsigned char* lds, const Gemm g, const Sched& S, const Epi& E, int tid) {
;     ...
;             const bool last = (t == nt - 2);
;             const char* a1 = cA + (size_t)(t + 1) * kstep;
;             const char* a2 = last ? nA : cA + (size_t)(t + 2) * kstep; const char* b2 = last ? nB : cB + (size_t)(t + 2) * kstep;
;             const char* a3 = a2 + kstep; const char* b3 = b2 + kstep;
;             PG8_LDB(B0, 0, 0); PG8_SCHED; PG8_LDA(At, 0, 0); PG8_STAGE(PG8_SA(1, 1), a1 + hstep, voffA);
;             PG8_WAIT_L(8); PG8_BAR; PG8_WAIT_L(0); PG8_MMA(0, 0, At, B0); PG8_BAR; PG8_SCHED;
;             PG8_LDB(B1, 0, 1); PG8_STAGE(PG8_SB(0, 0), b2, voffB);
;     ...
;             PG8_BAR; PG8_WAIT_L(0); PG8_MMA(1, 0, At, B0); PG8_BAR; PG8_SCHED;
;             PG8_STAGE(PG8_SB(1, 1), b3 + hstep, voffB);
;             PG8_WAIT_V(6); PG8_BAR; PG8_MMA(1, 1, At, B1); PG8_BAR;
	s_waitcnt lgkmcnt(0)
	v_mfma_f32_16x16x32_bf16 v[60:63], v[138:141], v[164:167], v[60:63]
	v_mfma_f32_16x16x32_bf16 v[56:59], v[150:153], v[164:167], v[56:59]
	v_mfma_f32_16x16x32_bf16 v[44:47], v[138:141], v[184:187], v[44:47]
	v_mfma_f32_16x16x32_bf16 v[40:43], v[150:153], v[184:187], v[40:43]
	v_mfma_f32_16x16x32_bf16 v[28:31], v[138:141], v[192:195], v[28:31]
	v_mfma_f32_16x16x32_bf16 v[24:27], v[150:153], v[192:195], v[24:27]
	v_mfma_f32_16x16x32_bf16 v[12:15], v[138:141], v[200:203], v[12:15]
	v_mfma_f32_16x16x32_bf16 v[8:11], v[150:153], v[200:203], v[8:11]
	v_mfma_f32_16x16x32_bf16 v[60:63], v[146:149], v[168:171], v[60:63]
	v_mfma_f32_16x16x32_bf16 v[56:59], v[160:163], v[168:171], v[56:59]
	v_mfma_f32_16x16x32_bf16 v[44:47], v[146:149], v[188:191], v[44:47]
	v_mfma_f32_16x16x32_bf16 v[40:43], v[160:163], v[188:191], v[40:43]
	v_mfma_f32_16x16x32_bf16 v[28:31], v[146:149], v[196:199], v[28:31]
	v_mfma_f32_16x16x32_bf16 v[24:27], v[160:163], v[196:199], v[24:27]
	v_mfma_f32_16x16x32_bf16 v[12:15], v[146:149], v[204:207], v[12:15]
	v_mfma_f32_16x16x32_bf16 v[8:11], v[160:163], v[204:207], v[8:11]
	s_barrier
	s_setprio 0
	s_add_u32 s0, s34, 0x40080
	s_addc_u32 s1, s35, 0
	s_add_i32 s17, s42, s45
	v_lshl_add_u64 v[138:139], s[0:1], 0, v[154:155]
	s_mov_b32 m0, s17
	s_nop 0
	global_load_lds_dwordx4 v[138:139], off
	v_lshl_add_u64 v[138:139], s[0:1], 0, v[128:129]
	s_add_i32 m0, s17, 0x2000
	s_nop 0
	global_load_lds_dwordx4 v[138:139], off
	s_waitcnt vmcnt(6)
	s_setprio 1
	s_barrier
	v_mfma_f32_16x16x32_bf16 v[52:55], v[208:211], v[164:167], v[52:55]
	v_mfma_f32_16x16x32_bf16 v[48:51], v[216:219], v[164:167], v[48:51]
	v_mfma_f32_16x16x32_bf16 v[36:39], v[208:211], v[184:187], v[36:39]
	v_mfma_f32_16x16x32_bf16 v[32:35], v[216:219], v[184:187], v[32:35]
	v_mfma_f32_16x16x32_bf16 v[20:23], v[208:211], v[192:195], v[20:23]
	v_mfma_f32_16x16x32_bf16 v[16:19], v[216:219], v[192:195], v[16:19]
	s_add_i32 s61, s61, 2
	v_mfma_f32_16x16x32_bf16 v[4:7], v[208:211], v[200:203], v[4:7]
	s_add_u32 s40, s40, 0x100
	v_mfma_f32_16x16x32_bf16 v[0:3], v[216:219], v[200:203], v[0:3]
	s_addc_u32 s41, s41, 0
	v_mfma_f32_16x16x32_bf16 v[52:55], v[212:215], v[168:171], v[52:55]
	s_add_u32 s58, s58, 0x100
	v_mfma_f32_16x16x32_bf16 v[48:51], v[220:223], v[168:171], v[48:51]
	s_addc_u32 s60, s60, 0
	v_mfma_f32_16x16x32_bf16 v[36:39], v[212:215], v[188:191], v[36:39]
	s_cmp_gt_u32 s61, 13
	v_mfma_f32_16x16x32_bf16 v[32:35], v[220:223], v[188:191], v[32:35]
	v_mfma_f32_16x16x32_bf16 v[20:23], v[212:215], v[196:199], v[20:23]
	v_mfma_f32_16x16x32_bf16 v[16:19], v[220:223], v[196:199], v[16:19]
	v_mfma_f32_16x16x32_bf16 v[4:7], v[212:215], v[204:207], v[4:7]
	v_mfma_f32_16x16x32_bf16 v[0:3], v[220:223], v[204:207], v[0:3]
	s_barrier
	s_setprio 0
	s_cbranch_scc1 .Lpeel_exit_swiglu
.LBB0_115:
	ds_read_b128 v[138:141], v240
	ds_read_b128 v[146:149], v240 offset:1024
	ds_read_b128 v[150:153], v240 offset:2048
	ds_read_b128 v[160:163], v240 offset:3072
	v_lshl_add_u64 v[208:209], s[40:41], 0, v[134:135]
	s_add_i32 m0, s39, 0xc000
	ds_read_b128 v[164:167], v145
	ds_read_b128 v[184:187], v145 offset:2048
	ds_read_b128 v[192:195], v145 offset:4096
	ds_read_b128 v[200:203], v145 offset:6144
	global_load_lds_dwordx4 v[208:209], off
	s_add_u32 s0, s40, 0xfffc0080
	s_addc_u32 s1, s41, -1
	s_add_i32 s17, 0, 0x10000
	s_cmp_eq_u32 s61, 12
	s_cselect_b32 s43, s25, s1
	s_cselect_b32 s42, s53, s0
	s_cselect_b32 s35, s15, s60
	s_cselect_b32 s34, s55, s58
	s_waitcnt lgkmcnt(4)
	s_setprio 1
	s_barrier
	s_waitcnt lgkmcnt(0)
	v_mfma_f32_16x16x32_bf16 v[124:127], v[138:141], v[164:167], v[124:127]
	ds_read_b128 v[168:171], v145 offset:1024
	v_mfma_f32_16x16x32_bf16 v[120:123], v[150:153], v[164:167], v[120:123]
	ds_read_b128 v[188:191], v145 offset:3072
	v_mfma_f32_16x16x32_bf16 v[108:111], v[138:141], v[184:187], v[108:111]
	ds_read_b128 v[196:199], v145 offset:5120
	v_mfma_f32_16x16x32_bf16 v[104:107], v[150:153], v[184:187], v[104:107]
	ds_read_b128 v[204:207], v145 offset:7168
	v_mfma_f32_16x16x32_bf16 v[92:95], v[138:141], v[192:195], v[92:95]
	v_mfma_f32_16x16x32_bf16 v[88:91], v[150:153], v[192:195], v[88:91]
	v_mfma_f32_16x16x32_bf16 v[76:79], v[138:141], v[200:203], v[76:79]
	v_mfma_f32_16x16x32_bf16 v[72:75], v[150:153], v[200:203], v[72:75]
	s_waitcnt lgkmcnt(0)
	v_mfma_f32_16x16x32_bf16 v[124:127], v[146:149], v[168:171], v[124:127]
	v_mfma_f32_16x16x32_bf16 v[120:123], v[160:163], v[168:171], v[120:123]
	v_mfma_f32_16x16x32_bf16 v[108:111], v[146:149], v[188:191], v[108:111]
	v_mfma_f32_16x16x32_bf16 v[104:107], v[160:163], v[188:191], v[104:107]
	v_mfma_f32_16x16x32_bf16 v[92:95], v[146:149], v[196:199], v[92:95]
	v_mfma_f32_16x16x32_bf16 v[88:91], v[160:163], v[196:199], v[88:91]
	v_mfma_f32_16x16x32_bf16 v[76:79], v[146:149], v[204:207], v[76:79]
	v_mfma_f32_16x16x32_bf16 v[72:75], v[160:163], v[204:207], v[72:75]
	s_barrier
	s_setprio 0
	v_lshl_add_u64 v[238:239], s[40:41], 0, v[136:137]
	s_add_i32 m0, s39, 0xe000
	s_nop 0
	global_load_lds_dwordx4 v[238:239], off
	s_add_i32 s63, 0, 0x14000
	s_add_i32 s0, s17, s45
	v_add_u32_e32 v183, s63, v143
	v_lshl_add_u64 v[224:225], s[34:35], 0, v[154:155]
	s_mov_b32 m0, s0
	ds_read_b128 v[208:211], v183
	ds_read_b128 v[212:215], v183 offset:1024
	ds_read_b128 v[216:219], v183 offset:2048
	ds_read_b128 v[220:223], v183 offset:3072
	global_load_lds_dwordx4 v[224:225], off
	v_lshl_add_u64 v[226:227], s[34:35], 0, v[128:129]
	s_add_i32 m0, s0, 0x2000
	s_nop 0
	global_load_lds_dwordx4 v[226:227], off
	s_setprio 1
	s_barrier
; #define PG8_STAGE(bufoff, gbase, voff) do { _Pragma("unroll") for (int _i = 0; _i < 2; ++_i) \
;         __builtin_amdgcn_global_load_lds((const unsigned*)((const char*)(gbase) + (voff)[_i]), (LAS unsigned*)(lds + (bufoff) + ldsw + _i * 8192), 16, 0, 0); } while (0)
; #define PG8_LDA(dst, b, h) do { _Pragma("unroll") for (int m = 0; m < 4; ++m) _Pragma("unroll") for (int k = 0; k < 2; ++k) dst[m][k] = *(const LAS bf16x8*)(lds + PG8_SA(b, h) + aoff + m * 2048 + k * 1024); } while (0)
; #define PG8_LDB(dst, b, h) do { _Pragma("unroll") for (int n = 0; n < 2; ++n) _Pragma("unroll") for (int k = 0; k < 2; ++k) dst[n][k] = *(const LAS bf16x8*)(lds + PG8_SB(b, h) + boff + n * 2048 + k * 1024); } while (0)
; #define PG8_MMA(ai, bj, At, Bt) do { __builtin_amdgcn_s_setprio(1); _Pragma("unroll") for (int m = 0; m < 4; ++m) _Pragma("unroll") for (int n = 0; n < 2; ++n) _Pragma("unroll") for (int k = 0; k < 2; ++k) \
;         acc[ai][bj][m][n] = __builtin_amdgcn_mfma_f32_16x16x32_bf16(Bt[n][k], At[m][k], acc[ai][bj][m][n], 0, 0, 0); __builtin_amdgcn_s_setprio(0); } while (0)
; #define PG8_WAIT_V(n) asm volatile("s_waitcnt vmcnt(" #n ")" ::: "memory")
; #define PG8_WAIT_L(n) asm volatile("s_waitcnt lgkmcnt(" #n ")" ::: "memory")
; #define PG8_BAR __builtin_amdgcn_s_barrier()
; #define PG8_SCHED __builtin_amdgcn_sched_barrier(0)
; template <class Epi, class Sched>
; __device__ __forceinline__ void gemm_phase(LAS unsigned char* lds, const Gemm g, const Sched& S, const Epi& E, int tid) {
;     ...
;             PG8_LDB(B1, 0, 1); PG8_STAGE(PG8_SB(0, 0), b2, voffB);
;             PG8_BAR; PG8_WAIT_L(0); PG8_MMA(0, 1, At, B1); PG8_BAR;
;             PG8_LDA(At, 0, 1); PG8_STAGE(PG8_SA(0, 0), a2, voffA);
;             PG8_BAR; PG8_WAIT_L(0); PG8_MMA(1, 0, At, B0); PG8_BAR; PG8_SCHED;
;             PG8_STAGE(PG8_SB(0, 1), b2 + hstep, voffB);
;             PG8_WAIT_V(6); PG8_BAR; PG8_MMA(1, 1, At, B1); PG8_BAR;
;             PG8_LDB(B0, 1, 0); PG8_SCHED; PG8_LDA(At, 1, 0); PG8_STAGE(PG8_SA(0, 1), a2 + hstep, voffA);
	s_waitcnt lgkmcnt(0)
	v_mfma_f32_16x16x32_bf16 v[116:119], v[208:211], v[164:167], v[116:119]
	v_mfma_f32_16x16x32_bf16 v[112:115], v[216:219], v[164:167], v[112:115]
	v_mfma_f32_16x16x32_bf16 v[100:103], v[208:211], v[184:187], v[100:103]
	v_mfma_f32_16x16x32_bf16 v[96:99], v[216:219], v[184:187], v[96:99]
	v_mfma_f32_16x16x32_bf16 v[84:87], v[208:211], v[192:195], v[84:87]
	v_mfma_f32_16x16x32_bf16 v[80:83], v[216:219], v[192:195], v[80:83]
	s_mov_b32 m0, s39
	v_mfma_f32_16x16x32_bf16 v[68:71], v[208:211], v[200:203], v[68:71]
	v_lshl_add_u64 v[228:229], s[42:43], 0, v[132:133]
	v_mfma_f32_16x16x32_bf16 v[64:67], v[216:219], v[200:203], v[64:67]
	v_mfma_f32_16x16x32_bf16 v[116:119], v[212:215], v[168:171], v[116:119]
	v_mfma_f32_16x16x32_bf16 v[112:115], v[220:223], v[168:171], v[112:115]
	v_mfma_f32_16x16x32_bf16 v[100:103], v[212:215], v[188:191], v[100:103]
	v_mfma_f32_16x16x32_bf16 v[96:99], v[220:223], v[188:191], v[96:99]
	v_mfma_f32_16x16x32_bf16 v[84:87], v[212:215], v[196:199], v[84:87]
	v_mfma_f32_16x16x32_bf16 v[80:83], v[220:223], v[196:199], v[80:83]
	v_mfma_f32_16x16x32_bf16 v[68:71], v[212:215], v[204:207], v[68:71]
	v_mfma_f32_16x16x32_bf16 v[64:67], v[220:223], v[204:207], v[64:67]
	s_barrier
	s_setprio 0
	ds_read_b128 v[164:167], v145 offset:16384
	ds_read_b128 v[168:171], v145 offset:17408
	ds_read_b128 v[184:187], v145 offset:18432
	ds_read_b128 v[188:191], v145 offset:19456
	ds_read_b128 v[192:195], v145 offset:20480
	ds_read_b128 v[196:199], v145 offset:21504
	ds_read_b128 v[200:203], v145 offset:22528
	ds_read_b128 v[204:207], v145 offset:23552
	global_load_lds_dwordx4 v[228:229], off
	v_lshl_add_u64 v[230:231], s[42:43], 0, v[130:131]
	s_mov_b32 m0, s47
	s_nop 0
	global_load_lds_dwordx4 v[230:231], off
	s_setprio 1
	s_barrier
	s_waitcnt lgkmcnt(0)
	v_mfma_f32_16x16x32_bf16 v[60:63], v[138:141], v[164:167], v[60:63]
	v_mfma_f32_16x16x32_bf16 v[56:59], v[150:153], v[164:167], v[56:59]
	v_mfma_f32_16x16x32_bf16 v[44:47], v[138:141], v[184:187], v[44:47]
	v_mfma_f32_16x16x32_bf16 v[40:43], v[150:153], v[184:187], v[40:43]
	v_mfma_f32_16x16x32_bf16 v[28:31], v[138:141], v[192:195], v[28:31]
	v_mfma_f32_16x16x32_bf16 v[24:27], v[150:153], v[192:195], v[24:27]
	v_mfma_f32_16x16x32_bf16 v[12:15], v[138:141], v[200:203], v[12:15]
	v_mfma_f32_16x16x32_bf16 v[8:11], v[150:153], v[200:203], v[8:11]
	v_mfma_f32_16x16x32_bf16 v[60:63], v[146:149], v[168:171], v[60:63]
	v_mfma_f32_16x16x32_bf16 v[56:59], v[160:163], v[168:171], v[56:59]
	v_mfma_f32_16x16x32_bf16 v[44:47], v[146:149], v[188:191], v[44:47]
	v_mfma_f32_16x16x32_bf16 v[40:43], v[160:163], v[188:191], v[40:43]
	v_mfma_f32_16x16x32_bf16 v[28:31], v[146:149], v[196:199], v[28:31]
	v_mfma_f32_16x16x32_bf16 v[24:27], v[160:163], v[196:199], v[24:27]
	v_mfma_f32_16x16x32_bf16 v[12:15], v[146:149], v[204:207], v[12:15]
	v_mfma_f32_16x16x32_bf16 v[8:11], v[160:163], v[204:207], v[8:11]
	s_barrier
	s_setprio 0
	s_add_u32 s0, s34, 0x40000
	s_addc_u32 s1, s35, 0
	s_add_i32 s17, s63, s45
	v_lshl_add_u64 v[138:139], s[0:1], 0, v[154:155]
	s_mov_b32 m0, s17
	s_nop 0
	global_load_lds_dwordx4 v[138:139], off
	v_lshl_add_u64 v[138:139], s[0:1], 0, v[128:129]
	s_add_i32 m0, s17, 0x2000
	s_nop 0
	global_load_lds_dwordx4 v[138:139], off
	s_waitcnt vmcnt(6)
	s_setprio 1
	s_barrier
	v_mfma_f32_16x16x32_bf16 v[52:55], v[208:211], v[164:167], v[52:55]
	v_mfma_f32_16x16x32_bf16 v[48:51], v[216:219], v[164:167], v[48:51]
	v_mfma_f32_16x16x32_bf16 v[36:39], v[208:211], v[184:187], v[36:39]
	v_mfma_f32_16x16x32_bf16 v[32:35], v[216:219], v[184:187], v[32:35]
	v_mfma_f32_16x16x32_bf16 v[20:23], v[208:211], v[192:195], v[20:23]
	v_mfma_f32_16x16x32_bf16 v[16:19], v[216:219], v[192:195], v[16:19]
	s_add_i32 s17, 0, 0x18000
	v_mfma_f32_16x16x32_bf16 v[4:7], v[208:211], v[200:203], v[4:7]
	v_add_u32_e32 v160, s17, v143
	v_mfma_f32_16x16x32_bf16 v[0:3], v[216:219], v[200:203], v[0:3]
	v_mfma_f32_16x16x32_bf16 v[52:55], v[212:215], v[168:171], v[52:55]
	v_mfma_f32_16x16x32_bf16 v[48:51], v[220:223], v[168:171], v[48:51]
	v_mfma_f32_16x16x32_bf16 v[36:39], v[212:215], v[188:191], v[36:39]
	v_mfma_f32_16x16x32_bf16 v[32:35], v[220:223], v[188:191], v[32:35]
	v_mfma_f32_16x16x32_bf16 v[20:23], v[212:215], v[196:199], v[20:23]
	v_mfma_f32_16x16x32_bf16 v[16:19], v[220:223], v[196:199], v[16:19]
	v_mfma_f32_16x16x32_bf16 v[4:7], v[212:215], v[204:207], v[4:7]
	v_mfma_f32_16x16x32_bf16 v[0:3], v[220:223], v[204:207], v[0:3]
	s_barrier
	s_setprio 0
	ds_read_b128 v[138:141], v160
	ds_read_b128 v[146:149], v160 offset:1024
	ds_read_b128 v[150:153], v160 offset:2048
	ds_read_b128 v[160:163], v160 offset:3072
	s_add_u32 s0, s42, 0x40000
	s_addc_u32 s1, s43, 0
	s_mov_b32 m0, s48
	v_lshl_add_u64 v[208:209], s[0:1], 0, v[132:133]
	ds_read_b128 v[164:167], v145 offset:32768
	ds_read_b128 v[184:187], v145 offset:34816
	ds_read_b128 v[192:195], v145 offset:36864
	ds_read_b128 v[200:203], v145 offset:38912
	global_load_lds_dwordx4 v[208:209], off
	s_waitcnt lgkmcnt(4)
	s_setprio 1
	s_barrier
; #define PG8_STAGE(bufoff, gbase, voff) do { _Pragma("unroll") for (int _i = 0; _i < 2; ++_i) \
;         __builtin_amdgcn_global_load_lds((const unsigned*)((const char*)(gbase) + (voff)[_i]), (LAS unsigned*)(lds + (bufoff) + ldsw + _i * 8192), 16, 0, 0); } while (0)
; #define PG8_LDA(dst, b, h) do { _Pragma("unroll") for (int m = 0; m < 4; ++m) _Pragma("unroll") for (int k = 0; k < 2; ++k) dst[m][k] = *(const LAS bf16x8*)(lds + PG8_SA(b, h) + aoff + m * 2048 + k * 1024); } while (0)
; #define PG8_LDB(dst, b, h) do { _Pragma("unroll") for (int n = 0; n < 2; ++n) _Pragma("unroll") for (int k = 0; k < 2; ++k) dst[n][k] = *(const LAS bf16x8*)(lds + PG8_SB(b, h) + boff + n * 2048 + k * 1024); } while (0)
; #define PG8_MMA(ai, bj, At, Bt) do { __builtin_amdgcn_s_setprio(1); _Pragma("unroll") for (int m = 0; m < 4; ++m) _Pragma("unroll") for (int n = 0; n < 2; ++n) _Pragma("unroll") for (int k = 0; k < 2; ++k) \
;         acc[ai][bj][m][n] = __builtin_amdgcn_mfma_f32_16x16x32_bf16(Bt[n][k], At[m][k], acc[ai][bj][m][n], 0, 0, 0); __builtin_amdgcn_s_setprio(0); } while (0)
; #define PG8_WAIT_V(n) asm volatile("s_waitcnt vmcnt(" #n ")" ::: "memory")
; #define PG8_WAIT_L(n) asm volatile("s_waitcnt lgkmcnt(" #n ")" ::: "memory")
; #define PG8_BAR __builtin_amdgcn_s_barrier()
; #define PG8_SCHED __builtin_amdgcn_sched_barrier(0)
; template <class Epi, class Sched>
; __device__ __forceinline__ void gemm_phase(LAS unsigned char* lds, const Gemm g, const Sched& S, const Epi& E, int tid) {
;     ...
;             PG8_LDB(B0, 1, 0); PG8_SCHED; PG8_LDA(At, 1, 0); PG8_STAGE(PG8_SA(0, 1), a2 + hstep, voffA);
;             PG8_WAIT_L(8); PG8_BAR; PG8_WAIT_L(0); PG8_MMA(0, 0, At, B0); PG8_BAR; PG8_SCHED;
;             PG8_LDB(B1, 1, 1); PG8_STAGE(PG8_SB(1, 0), b3, voffB);
;             PG8_BAR; PG8_WAIT_L(0); PG8_MMA(0, 1, At, B1); PG8_BAR;
;             PG8_LDA(At, 1, 1); PG8_STAGE(PG8_SA(1, 0), a3, voffA);
;             PG8_BAR; PG8_WAIT_L(0); PG8_MMA(1, 0, At, B0); PG8_BAR; PG8_SCHED;
;             PG8_STAGE(PG8_SB(1, 1), b3 + hstep, voffB);
;             PG8_WAIT_V(6); PG8_BAR; PG8_MMA(1, 1, At, B1); PG8_BAR;
	s_waitcnt lgkmcnt(0)
	v_mfma_f32_16x16x32_bf16 v[124:127], v[138:141], v[164:167], v[124:127]
	ds_read_b128 v[168:171], v145 offset:33792
	v_mfma_f32_16x16x32_bf16 v[120:123], v[150:153], v[164:167], v[120:123]
	ds_read_b128 v[188:191], v145 offset:35840
	v_mfma_f32_16x16x32_bf16 v[108:111], v[138:141], v[184:187], v[108:111]
	ds_read_b128 v[196:199], v145 offset:37888
	v_mfma_f32_16x16x32_bf16 v[104:107], v[150:153], v[184:187], v[104:107]
	ds_read_b128 v[204:207], v145 offset:39936
	v_mfma_f32_16x16x32_bf16 v[92:95], v[138:141], v[192:195], v[92:95]
	v_mfma_f32_16x16x32_bf16 v[88:91], v[150:153], v[192:195], v[88:91]
	v_mfma_f32_16x16x32_bf16 v[76:79], v[138:141], v[200:203], v[76:79]
	v_mfma_f32_16x16x32_bf16 v[72:75], v[150:153], v[200:203], v[72:75]
	s_waitcnt lgkmcnt(0)
	v_mfma_f32_16x16x32_bf16 v[124:127], v[146:149], v[168:171], v[124:127]
	v_mfma_f32_16x16x32_bf16 v[120:123], v[160:163], v[168:171], v[120:123]
	v_mfma_f32_16x16x32_bf16 v[108:111], v[146:149], v[188:191], v[108:111]
	v_mfma_f32_16x16x32_bf16 v[104:107], v[160:163], v[188:191], v[104:107]
	v_mfma_f32_16x16x32_bf16 v[92:95], v[146:149], v[196:199], v[92:95]
	v_mfma_f32_16x16x32_bf16 v[88:91], v[160:163], v[196:199], v[88:91]
	v_mfma_f32_16x16x32_bf16 v[76:79], v[146:149], v[204:207], v[76:79]
	v_mfma_f32_16x16x32_bf16 v[72:75], v[160:163], v[204:207], v[72:75]
	s_barrier
	s_setprio 0
	v_lshl_add_u64 v[238:239], s[0:1], 0, v[130:131]
	s_mov_b32 m0, s49
	s_nop 0
	global_load_lds_dwordx4 v[238:239], off
	s_add_i32 s42, 0, 0x1c000
	s_add_i32 s0, s17, s45
	v_add_u32_e32 v183, s42, v143
	v_lshl_add_u64 v[224:225], v[224:225], 0, s[8:9]
	s_mov_b32 m0, s0
	ds_read_b128 v[208:211], v183
	ds_read_b128 v[212:215], v183 offset:1024
	ds_read_b128 v[216:219], v183 offset:2048
	ds_read_b128 v[220:223], v183 offset:3072
	global_load_lds_dwordx4 v[224:225], off
	v_lshl_add_u64 v[224:225], v[226:227], 0, s[8:9]
	s_add_i32 m0, s0, 0x2000
	s_nop 0
	global_load_lds_dwordx4 v[224:225], off
	s_setprio 1
	s_barrier
	s_waitcnt lgkmcnt(0)
	v_mfma_f32_16x16x32_bf16 v[116:119], v[208:211], v[164:167], v[116:119]
	v_mfma_f32_16x16x32_bf16 v[112:115], v[216:219], v[164:167], v[112:115]
	v_mfma_f32_16x16x32_bf16 v[100:103], v[208:211], v[184:187], v[100:103]
	v_mfma_f32_16x16x32_bf16 v[96:99], v[216:219], v[184:187], v[96:99]
	v_mfma_f32_16x16x32_bf16 v[84:87], v[208:211], v[192:195], v[84:87]
	v_mfma_f32_16x16x32_bf16 v[80:83], v[216:219], v[192:195], v[80:83]
	s_mov_b32 m0, s6
	v_mfma_f32_16x16x32_bf16 v[68:71], v[208:211], v[200:203], v[68:71]
	v_lshl_add_u64 v[224:225], v[228:229], 0, s[8:9]
	v_mfma_f32_16x16x32_bf16 v[64:67], v[216:219], v[200:203], v[64:67]
	v_mfma_f32_16x16x32_bf16 v[116:119], v[212:215], v[168:171], v[116:119]
	v_mfma_f32_16x16x32_bf16 v[112:115], v[220:223], v[168:171], v[112:115]
	v_mfma_f32_16x16x32_bf16 v[100:103], v[212:215], v[188:191], v[100:103]
	v_mfma_f32_16x16x32_bf16 v[96:99], v[220:223], v[188:191], v[96:99]
	v_mfma_f32_16x16x32_bf16 v[84:87], v[212:215], v[196:199], v[84:87]
	v_mfma_f32_16x16x32_bf16 v[80:83], v[220:223], v[196:199], v[80:83]
	v_mfma_f32_16x16x32_bf16 v[68:71], v[212:215], v[204:207], v[68:71]
	v_mfma_f32_16x16x32_bf16 v[64:67], v[220:223], v[204:207], v[64:67]
	s_barrier
	s_setprio 0
	ds_read_b128 v[164:167], v145 offset:49152
	ds_read_b128 v[168:171], v145 offset:50176
	ds_read_b128 v[184:187], v145 offset:51200
	ds_read_b128 v[188:191], v145 offset:52224
	ds_read_b128 v[192:195], v145 offset:53248
	ds_read_b128 v[196:199], v145 offset:54272
	ds_read_b128 v[200:203], v145 offset:55296
	ds_read_b128 v[204:207], v145 offset:56320
	global_load_lds_dwordx4 v[224:225], off
	v_lshl_add_u64 v[224:225], v[230:231], 0, s[8:9]
	s_mov_b32 m0, s50
	s_nop 0
	global_load_lds_dwordx4 v[224:225], off
	s_setprio 1
	s_barrier
	s_waitcnt lgkmcnt(0)
	v_mfma_f32_16x16x32_bf16 v[60:63], v[138:141], v[164:167], v[60:63]
	v_mfma_f32_16x16x32_bf16 v[56:59], v[150:153], v[164:167], v[56:59]
	v_mfma_f32_16x16x32_bf16 v[44:47], v[138:141], v[184:187], v[44:47]
	v_mfma_f32_16x16x32_bf16 v[40:43], v[150:153], v[184:187], v[40:43]
	v_mfma_f32_16x16x32_bf16 v[28:31], v[138:141], v[192:195], v[28:31]
	v_mfma_f32_16x16x32_bf16 v[24:27], v[150:153], v[192:195], v[24:27]
	v_mfma_f32_16x16x32_bf16 v[12:15], v[138:141], v[200:203], v[12:15]
	v_mfma_f32_16x16x32_bf16 v[8:11], v[150:153], v[200:203], v[8:11]
	v_mfma_f32_16x16x32_bf16 v[60:63], v[146:149], v[168:171], v[60:63]
	v_mfma_f32_16x16x32_bf16 v[56:59], v[160:163], v[168:171], v[56:59]
	v_mfma_f32_16x16x32_bf16 v[44:47], v[146:149], v[188:191], v[44:47]
	v_mfma_f32_16x16x32_bf16 v[40:43], v[160:163], v[188:191], v[40:43]
	v_mfma_f32_16x16x32_bf16 v[28:31], v[146:149], v[196:199], v[28:31]
	v_mfma_f32_16x16x32_bf16 v[24:27], v[160:163], v[196:199], v[24:27]
	v_mfma_f32_16x16x32_bf16 v[12:15], v[146:149], v[204:207], v[12:15]
	v_mfma_f32_16x16x32_bf16 v[8:11], v[160:163], v[204:207], v[8:11]
	s_barrier
	s_setprio 0
	s_add_u32 s0, s34, 0x40080
	s_addc_u32 s1, s35, 0
	s_add_i32 s17, s42, s45
	v_lshl_add_u64 v[138:139], s[0:1], 0, v[154:155]
	s_mov_b32 m0, s17
	s_nop 0
	global_load_lds_dwordx4 v[138:139], off
	v_lshl_add_u64 v[138:139], s[0:1], 0, v[128:129]
	s_add_i32 m0, s17, 0x2000
	s_nop 0
	global_load_lds_dwordx4 v[138:139], off
	s_waitcnt vmcnt(6)
	s_setprio 1
	s_barrier
	v_mfma_f32_16x16x32_bf16 v[52:55], v[208:211], v[164:167], v[52:55]
	v_mfma_f32_16x16x32_bf16 v[48:51], v[216:219], v[164:167], v[48:51]
	v_mfma_f32_16x16x32_bf16 v[36:39], v[208:211], v[184:187], v[36:39]
	v_mfma_f32_16x16x32_bf16 v[32:35], v[216:219], v[184:187], v[32:35]
	v_mfma_f32_16x16x32_bf16 v[20:23], v[208:211], v[192:195], v[20:23]
	v_mfma_f32_16x16x32_bf16 v[16:19], v[216:219], v[192:195], v[16:19]
	s_add_i32 s61, s61, 2
	v_mfma_f32_16x16x32_bf16 v[4:7], v[208:211], v[200:203], v[4:7]
	s_add_u32 s40, s40, 0x100
	v_mfma_f32_16x16x32_bf16 v[0:3], v[216:219], v[200:203], v[0:3]
	s_addc_u32 s41, s41, 0
	v_mfma_f32_16x16x32_bf16 v[52:55], v[212:215], v[168:171], v[52:55]
	s_add_u32 s58, s58, 0x100
	v_mfma_f32_16x16x32_bf16 v[48:51], v[220:223], v[168:171], v[48:51]
	s_addc_u32 s60, s60, 0
	v_mfma_f32_16x16x32_bf16 v[36:39], v[212:215], v[188:191], v[36:39]
	s_cmp_gt_u32 s61, 13
	v_mfma_f32_16x16x32_bf16 v[32:35], v[220:223], v[188:191], v[32:35]
	v_mfma_f32_16x16x32_bf16 v[20:23], v[212:215], v[196:199], v[20:23]
	v_mfma_f32_16x16x32_bf16 v[16:19], v[220:223], v[196:199], v[16:19]
	v_mfma_f32_16x16x32_bf16 v[4:7], v[212:215], v[204:207], v[4:7]
	v_mfma_f32_16x16x32_bf16 v[0:3], v[220:223], v[204:207], v[0:3]
	s_barrier
	s_setprio 0
	s_cbranch_scc0 .LBB0_115
